# v1 + hand-written P0b (double-buffered rows+params, single counted wait per iteration, DPP reduction)
# speedup vs baseline: 1.0044x; 1.0044x over previous
; #define P0B_LOAD(dst_, r0_) do { _Pragma("unroll") for (int rr = 0; rr < 2; ++rr) { const int row = min((r0_) + rr * NGW, NTOK - 1); \
;             const float* xr = row < NP ? P.xp + (size_t)row * DM : P.xs + (size_t)(row - NP) * DM; \
;             _Pragma("unroll") for (int j = 0; j < 4; ++j) dst_[rr][j] = *(const f32x4*)(xr + 8 * lane + 512 * (j >> 1) + 4 * (j & 1)); } } while (0)
; __device__ __forceinline__ void phase0b(const Params& P, int lane, int wave, int bid, int G) {
;     const float* mod = (const float*)(P.ws + OFF_MOD); bf16_t* H = (bf16_t*)(P.ws + OFF_H);
;     const int gw = bid * 8 + wave, NGW = G * 8;
;     f32x4 v[2][4], vn[2][4];
;     ...
;     P0B_LOAD(v, gw);
;     for (int row0 = gw; row0 < NTOK; row0 += 2 * NGW) {
;         P0B_LOAD(vn, row0 + 2 * NGW);
;         asm volatile("" ::: "memory");
;         float ss[2];
; #pragma unroll
;         for (int rr = 0; rr < 2; ++rr) { float s2 = 0.f;
; #pragma unroll
;             for (int j = 0; j < 4; ++j) s2 += (v[rr][j].x * v[rr][j].x + v[rr][j].y * v[rr][j].y) + (v[rr][j].z * v[rr][j].z + v[rr][j].w * v[rr][j].w);
;             ss[rr] = s2; }
; #pragma unroll
;         for (int rr = 0; rr < 2; ++rr) { const int row = row0 + rr * NGW; if (row >= NTOK) break;
;             const int s = row < NP ? (row >> 12) : 16; const float* md = mod + s * 3072;
;             const float rstd = rsqrtf(wave_sum(ss[rr]) * (1.f / DM) + EPS);
.LBB0_90:
	s_cmp_lt_i32 s28, 2
	s_cselect_b64 s[0:1], -1, 0
	s_and_b64 s[4:5], s[0:1], s[6:7]
	s_andn2_b64 vcc, exec, s[4:5]
	s_cbranch_vccnz .LBB0_96
	s_lshl_b32 s16, s2, 3
	s_add_i32 s6, s97, s16
	s_cmp_gt_i32 s6, 0x13fff
	s_cbranch_scc1 .LBB0_96
	s_cmp_lg_u32 s3, 0x100
	s_cbranch_scc1 .Lp0b_generic
	v_lshlrev_b32_e32 v1, 5, v180
	v_lshlrev_b32_e32 v2, 4, v180
	v_mov_b32_e32 v3, 0x358637bd
	s_lshl_b32 vcc_lo, s6, 12
	s_add_u32 s4, s36, vcc_lo
	s_addc_u32 s5, s37, 0
	s_add_u32 s6, s4, 0x800000
	s_addc_u32 s7, s5, 0
	s_add_u32 s20, s38, vcc_lo
	s_addc_u32 s21, s39, 0
	s_lshr_b32 vcc_lo, vcc_lo, 1
	s_add_u32 s10, s22, 0x2000000
	s_addc_u32 s11, s23, 0
	s_add_u32 s10, s10, vcc_lo
	s_addc_u32 s11, s11, 0
	s_add_u32 s12, s10, 0x400000
	s_addc_u32 s13, s11, 0
	s_add_u32 s24, s22, 0x10000
	s_addc_u32 s19, s23, 0
	s_mov_b32 s14, s24
	s_mov_b32 s15, s19
	s_add_u32 s16, s14, 0x1000
	s_addc_u32 s17, s15, 0
	s_mov_b32 s18, 0
	global_load_dwordx4 v[4:7], v1, s[44:45] offset:0
	global_load_dwordx4 v[8:11], v1, s[44:45] offset:16
	global_load_dwordx4 v[12:15], v1, s[44:45] offset:2048
	global_load_dwordx4 v[16:19], v1, s[44:45] offset:2064
	global_load_dwordx4 v[36:39], v1, s[4:5] offset:0
	global_load_dwordx4 v[40:43], v1, s[4:5] offset:16
	global_load_dwordx4 v[44:47], v1, s[4:5] offset:2048
	global_load_dwordx4 v[48:51], v1, s[4:5] offset:2064
	global_load_dwordx4 v[52:55], v1, s[6:7] offset:0
	global_load_dwordx4 v[56:59], v1, s[6:7] offset:16
	global_load_dwordx4 v[60:63], v1, s[6:7] offset:2048
	global_load_dwordx4 v[64:67], v1, s[6:7] offset:2064
	global_load_dwordx4 v[68:71], v1, s[14:15] offset:0
	global_load_dwordx4 v[72:75], v1, s[14:15] offset:16
	global_load_dwordx4 v[76:79], v1, s[14:15] offset:2048
	global_load_dwordx4 v[80:83], v1, s[14:15] offset:2064
	global_load_dwordx4 v[84:87], v1, s[16:17] offset:0
	global_load_dwordx4 v[88:91], v1, s[16:17] offset:16
	global_load_dwordx4 v[92:95], v1, s[16:17] offset:2048
	global_load_dwordx4 v[96:99], v1, s[16:17] offset:2064
	s_add_u32 s4, s4, 0x1000000
	s_addc_u32 s5, s5, 0
	s_add_u32 s6, s4, 0x800000
	s_addc_u32 s7, s5, 0
	s_add_u32 s14, s24, 0x3000
	s_addc_u32 s15, s19, 0
	s_add_u32 s16, s14, 0x1000
	s_addc_u32 s17, s15, 0
	global_load_dwordx4 v[100:103], v1, s[4:5] offset:0
	global_load_dwordx4 v[104:107], v1, s[4:5] offset:16
	global_load_dwordx4 v[108:111], v1, s[4:5] offset:2048
	global_load_dwordx4 v[112:115], v1, s[4:5] offset:2064
	global_load_dwordx4 v[116:119], v1, s[6:7] offset:0
	global_load_dwordx4 v[120:123], v1, s[6:7] offset:16
	global_load_dwordx4 v[124:127], v1, s[6:7] offset:2048
	global_load_dwordx4 v[128:131], v1, s[6:7] offset:2064
	global_load_dwordx4 v[132:135], v1, s[14:15] offset:0
	global_load_dwordx4 v[136:139], v1, s[14:15] offset:16
	global_load_dwordx4 v[140:143], v1, s[14:15] offset:2048
	global_load_dwordx4 v[144:147], v1, s[14:15] offset:2064
	global_load_dwordx4 v[148:151], v1, s[16:17] offset:0
	global_load_dwordx4 v[152:155], v1, s[16:17] offset:16
	global_load_dwordx4 v[156:159], v1, s[16:17] offset:2048
	global_load_dwordx4 v[160:163], v1, s[16:17] offset:2064
	s_add_u32 s4, s4, 0x1000000
	s_addc_u32 s5, s5, 0
	s_cmp_eq_u32 s18, 14
	s_cselect_b32 s4, s20, s4
	s_cselect_b32 s5, s21, s5
	s_add_u32 s6, s4, 0x800000
	s_addc_u32 s7, s5, 0
	s_add_i32 vcc_lo, s18, 2
	s_min_u32 vcc_lo, vcc_lo, 16
	s_mul_i32 vcc_lo, vcc_lo, 0x3000
	s_add_u32 s14, s24, vcc_lo
	s_addc_u32 s15, s19, 0
	s_add_u32 s16, s14, 0x1000
	s_addc_u32 s17, s15, 0
	s_waitcnt vmcnt(16)
	v_pk_mul_f32 v[214:215], v[36:37], v[36:37]
	v_pk_mul_f32 v[222:223], v[52:53], v[52:53]
	v_pk_fma_f32 v[214:215], v[38:39], v[38:39], v[214:215]
	v_pk_fma_f32 v[222:223], v[54:55], v[54:55], v[222:223]
	v_pk_fma_f32 v[214:215], v[40:41], v[40:41], v[214:215]
	v_pk_fma_f32 v[222:223], v[56:57], v[56:57], v[222:223]
	v_pk_fma_f32 v[214:215], v[42:43], v[42:43], v[214:215]
	v_pk_fma_f32 v[222:223], v[58:59], v[58:59], v[222:223]
	v_pk_fma_f32 v[214:215], v[44:45], v[44:45], v[214:215]
	v_pk_fma_f32 v[222:223], v[60:61], v[60:61], v[222:223]
	v_pk_fma_f32 v[214:215], v[46:47], v[46:47], v[214:215]
	v_pk_fma_f32 v[222:223], v[62:63], v[62:63], v[222:223]
	v_pk_fma_f32 v[214:215], v[48:49], v[48:49], v[214:215]
	v_pk_fma_f32 v[222:223], v[64:65], v[64:65], v[222:223]
	v_pk_fma_f32 v[214:215], v[50:51], v[50:51], v[214:215]
	v_pk_fma_f32 v[222:223], v[66:67], v[66:67], v[222:223]
	v_add_f32_e32 v216, v214, v215
	v_add_f32_e32 v224, v222, v223
	v_pk_add_f32 v[20:21], v[84:85], 1.0 op_sel_hi:[1,0]
	v_pk_add_f32 v[22:23], v[86:87], 1.0 op_sel_hi:[1,0]
	v_add_f32_dpp v217, v216, v216 quad_perm:[1,0,3,2] row_mask:0xf bank_mask:0xf
	v_add_f32_dpp v225, v224, v224 quad_perm:[1,0,3,2] row_mask:0xf bank_mask:0xf
	v_pk_add_f32 v[24:25], v[88:89], 1.0 op_sel_hi:[1,0]
	v_pk_add_f32 v[26:27], v[90:91], 1.0 op_sel_hi:[1,0]
	v_add_f32_dpp v218, v217, v217 quad_perm:[2,3,0,1] row_mask:0xf bank_mask:0xf
	v_add_f32_dpp v226, v225, v225 quad_perm:[2,3,0,1] row_mask:0xf bank_mask:0xf
	v_pk_add_f32 v[28:29], v[92:93], 1.0 op_sel_hi:[1,0]
	v_pk_add_f32 v[30:31], v[94:95], 1.0 op_sel_hi:[1,0]
	v_add_f32_dpp v217, v218, v218 row_half_mirror row_mask:0xf bank_mask:0xf
	v_add_f32_dpp v225, v226, v226 row_half_mirror row_mask:0xf bank_mask:0xf
	v_pk_add_f32 v[32:33], v[96:97], 1.0 op_sel_hi:[1,0]
	v_pk_add_f32 v[34:35], v[98:99], 1.0 op_sel_hi:[1,0]
	v_add_f32_dpp v218, v217, v217 row_mirror row_mask:0xf bank_mask:0xf
	v_add_f32_dpp v226, v225, v225 row_mirror row_mask:0xf bank_mask:0xf
	s_nop 0
	s_nop 0
	v_mov_b32_e32 v219, v218
	v_mov_b32_e32 v227, v226
	s_nop 0
	s_nop 0
	v_permlane16_swap_b32_e32 v218, v219
	v_permlane16_swap_b32_e32 v226, v227
; __device__ __forceinline__ unsigned cvt_pk_bf16(float lo, float hi) { unsigned r; asm volatile("v_cvt_pk_bf16_f32 %0, %1, %2" : "=v"(r) : "v"(lo), "v"(hi)); return r; }
; #define P0B_LOAD(dst_, r0_) do { _Pragma("unroll") for (int rr = 0; rr < 2; ++rr) { const int row = min((r0_) + rr * NGW, NTOK - 1); \
;             const float* xr = row < NP ? P.xp + (size_t)row * DM : P.xs + (size_t)(row - NP) * DM; \
;             _Pragma("unroll") for (int j = 0; j < 4; ++j) dst_[rr][j] = *(const f32x4*)(xr + 8 * lane + 512 * (j >> 1) + 4 * (j & 1)); } } while (0)
; __device__ __forceinline__ void phase0b(const Params& P, int lane, int wave, int bid, int G) {
;     ...
;     P0B_LOAD(v, gw);
;     for (int row0 = gw; row0 < NTOK; row0 += 2 * NGW) {
;         P0B_LOAD(vn, row0 + 2 * NGW);
;     ...
;         for (int rr = 0; rr < 2; ++rr) { const int row = row0 + rr * NGW; if (row >= NTOK) break;
;             const int s = row < NP ? (row >> 12) : 16; const float* md = mod + s * 3072;
;             const float rstd = rsqrtf(wave_sum(ss[rr]) * (1.f / DM) + EPS);
; #pragma unroll
;             for (int jj = 0; jj < 2; ++jj) { const int c = 8 * lane + 512 * jj; f32x4 hv[2];
; #pragma unroll
;                 for (int e = 0; e < 2; ++e) { const f32x4 gn = *(const f32x4*)(P.norm_gain + c + 4 * e), sh = *(const f32x4*)(md + c + 4 * e), scv = *(const f32x4*)(md + 1024 + c + 4 * e);
;                     hv[e] = (v[rr][2 * jj + e] * rstd * gn) * (scv + 1.f) + sh; }
;                 u32x4 o; o.x = cvt_pk_bf16(hv[0].x, hv[0].y); o.y = cvt_pk_bf16(hv[0].z, hv[0].w); o.z = cvt_pk_bf16(hv[1].x, hv[1].y); o.w = cvt_pk_bf16(hv[1].z, hv[1].w);
;                 *(u32x4*)(H + (size_t)row * DM + c) = o; } }
	v_add_f32_e32 v218, v218, v219
	v_add_f32_e32 v226, v226, v227
	v_mov_b32_e32 v219, v218
	v_mov_b32_e32 v227, v226
	s_nop 0
	s_nop 0
	v_permlane32_swap_b32_e32 v218, v219
	v_permlane32_swap_b32_e32 v226, v227
	v_add_f32_e32 v218, v218, v219
	v_add_f32_e32 v226, v226, v227
	v_fmamk_f32 v220, v218, 0x3a800000, v3
	v_fmamk_f32 v228, v226, 0x3a800000, v3
	v_rsq_f32_e32 v220, v220
	v_rsq_f32_e32 v228, v228
	s_nop 0
	v_pk_mul_f32 v[164:165], v[36:37], v[220:221] op_sel_hi:[1,0]
	v_pk_mul_f32 v[166:167], v[38:39], v[220:221] op_sel_hi:[1,0]
	v_pk_mul_f32 v[168:169], v[40:41], v[220:221] op_sel_hi:[1,0]
	v_pk_mul_f32 v[170:171], v[42:43], v[220:221] op_sel_hi:[1,0]
	v_pk_mul_f32 v[172:173], v[44:45], v[220:221] op_sel_hi:[1,0]
	v_pk_mul_f32 v[174:175], v[46:47], v[220:221] op_sel_hi:[1,0]
	v_pk_mul_f32 v[176:177], v[48:49], v[220:221] op_sel_hi:[1,0]
	v_pk_mul_f32 v[178:179], v[50:51], v[220:221] op_sel_hi:[1,0]
	v_pk_mul_f32 v[164:165], v[4:5], v[164:165]
	v_pk_mul_f32 v[166:167], v[6:7], v[166:167]
	v_pk_mul_f32 v[168:169], v[8:9], v[168:169]
	v_pk_mul_f32 v[170:171], v[10:11], v[170:171]
	v_pk_mul_f32 v[172:173], v[12:13], v[172:173]
	v_pk_mul_f32 v[174:175], v[14:15], v[174:175]
	v_pk_mul_f32 v[176:177], v[16:17], v[176:177]
	v_pk_mul_f32 v[178:179], v[18:19], v[178:179]
	v_pk_fma_f32 v[164:165], v[20:21], v[164:165], v[68:69]
	v_pk_fma_f32 v[166:167], v[22:23], v[166:167], v[70:71]
	v_pk_fma_f32 v[168:169], v[24:25], v[168:169], v[72:73]
	v_pk_fma_f32 v[170:171], v[26:27], v[170:171], v[74:75]
	v_pk_fma_f32 v[172:173], v[28:29], v[172:173], v[76:77]
	v_pk_fma_f32 v[174:175], v[30:31], v[174:175], v[78:79]
	v_pk_fma_f32 v[176:177], v[32:33], v[176:177], v[80:81]
	v_pk_fma_f32 v[178:179], v[34:35], v[178:179], v[82:83]
	v_cvt_pk_bf16_f32 v198, v164, v165
	v_cvt_pk_bf16_f32 v199, v166, v167
	v_cvt_pk_bf16_f32 v200, v168, v169
	v_cvt_pk_bf16_f32 v201, v170, v171
	v_cvt_pk_bf16_f32 v202, v172, v173
	v_cvt_pk_bf16_f32 v203, v174, v175
	v_cvt_pk_bf16_f32 v204, v176, v177
	v_cvt_pk_bf16_f32 v205, v178, v179
	v_pk_mul_f32 v[182:183], v[52:53], v[228:229] op_sel_hi:[1,0]
	v_pk_mul_f32 v[184:185], v[54:55], v[228:229] op_sel_hi:[1,0]
	v_pk_mul_f32 v[186:187], v[56:57], v[228:229] op_sel_hi:[1,0]
	v_pk_mul_f32 v[188:189], v[58:59], v[228:229] op_sel_hi:[1,0]
	v_pk_mul_f32 v[190:191], v[60:61], v[228:229] op_sel_hi:[1,0]
	v_pk_mul_f32 v[192:193], v[62:63], v[228:229] op_sel_hi:[1,0]
	v_pk_mul_f32 v[194:195], v[64:65], v[228:229] op_sel_hi:[1,0]
	v_pk_mul_f32 v[196:197], v[66:67], v[228:229] op_sel_hi:[1,0]
	v_pk_mul_f32 v[182:183], v[4:5], v[182:183]
	v_pk_mul_f32 v[184:185], v[6:7], v[184:185]
	v_pk_mul_f32 v[186:187], v[8:9], v[186:187]
	v_pk_mul_f32 v[188:189], v[10:11], v[188:189]
	v_pk_mul_f32 v[190:191], v[12:13], v[190:191]
	v_pk_mul_f32 v[192:193], v[14:15], v[192:193]
	v_pk_mul_f32 v[194:195], v[16:17], v[194:195]
	v_pk_mul_f32 v[196:197], v[18:19], v[196:197]
	v_pk_fma_f32 v[182:183], v[20:21], v[182:183], v[68:69]
	v_pk_fma_f32 v[184:185], v[22:23], v[184:185], v[70:71]
	v_pk_fma_f32 v[186:187], v[24:25], v[186:187], v[72:73]
	v_pk_fma_f32 v[188:189], v[26:27], v[188:189], v[74:75]
	v_pk_fma_f32 v[190:191], v[28:29], v[190:191], v[76:77]
	v_pk_fma_f32 v[192:193], v[30:31], v[192:193], v[78:79]
	v_pk_fma_f32 v[194:195], v[32:33], v[194:195], v[80:81]
	v_pk_fma_f32 v[196:197], v[34:35], v[196:197], v[82:83]
	v_cvt_pk_bf16_f32 v206, v182, v183
	v_cvt_pk_bf16_f32 v207, v184, v185
	v_cvt_pk_bf16_f32 v208, v186, v187
	v_cvt_pk_bf16_f32 v209, v188, v189
	v_cvt_pk_bf16_f32 v210, v190, v191
	v_cvt_pk_bf16_f32 v211, v192, v193
	v_cvt_pk_bf16_f32 v212, v194, v195
	v_cvt_pk_bf16_f32 v213, v196, v197
	global_store_dwordx4 v2, v[198:201], s[10:11]
	global_store_dwordx4 v2, v[202:205], s[10:11] offset:1024
	global_store_dwordx4 v2, v[206:209], s[12:13]
	global_store_dwordx4 v2, v[210:213], s[12:13] offset:1024
	s_add_u32 s10, s10, 0x800000
	s_addc_u32 s11, s11, 0
	s_add_u32 s12, s12, 0x800000
	s_addc_u32 s13, s13, 0
	s_add_i32 s18, s18, 1
.Lp0b_loop:
	global_load_dwordx4 v[36:39], v1, s[4:5] offset:0
	global_load_dwordx4 v[40:43], v1, s[4:5] offset:16
	global_load_dwordx4 v[44:47], v1, s[4:5] offset:2048
	global_load_dwordx4 v[48:51], v1, s[4:5] offset:2064
	global_load_dwordx4 v[52:55], v1, s[6:7] offset:0
	global_load_dwordx4 v[56:59], v1, s[6:7] offset:16
	global_load_dwordx4 v[60:63], v1, s[6:7] offset:2048
	global_load_dwordx4 v[64:67], v1, s[6:7] offset:2064
	global_load_dwordx4 v[68:71], v1, s[14:15] offset:0
	global_load_dwordx4 v[72:75], v1, s[14:15] offset:16
	global_load_dwordx4 v[76:79], v1, s[14:15] offset:2048
	global_load_dwordx4 v[80:83], v1, s[14:15] offset:2064
	global_load_dwordx4 v[84:87], v1, s[16:17] offset:0
	global_load_dwordx4 v[88:91], v1, s[16:17] offset:16
	global_load_dwordx4 v[92:95], v1, s[16:17] offset:2048
	global_load_dwordx4 v[96:99], v1, s[16:17] offset:2064
	s_add_u32 s4, s4, 0x1000000
	s_addc_u32 s5, s5, 0
	s_cmp_eq_u32 s18, 14
	s_cselect_b32 s4, s20, s4
	s_cselect_b32 s5, s21, s5
	s_add_u32 s6, s4, 0x800000
	s_addc_u32 s7, s5, 0
	s_add_i32 vcc_lo, s18, 2
	s_min_u32 vcc_lo, vcc_lo, 16
	s_mul_i32 vcc_lo, vcc_lo, 0x3000
	s_add_u32 s14, s24, vcc_lo
	s_addc_u32 s15, s19, 0
	s_add_u32 s16, s14, 0x1000
	s_addc_u32 s17, s15, 0
	s_waitcnt vmcnt(20)
; __device__ __forceinline__ void phase0b(const Params& P, int lane, int wave, int bid, int G) {
;     ...
;         for (int rr = 0; rr < 2; ++rr) { float s2 = 0.f;
; #pragma unroll
;             for (int j = 0; j < 4; ++j) s2 += (v[rr][j].x * v[rr][j].x + v[rr][j].y * v[rr][j].y) + (v[rr][j].z * v[rr][j].z + v[rr][j].w * v[rr][j].w);
;             ss[rr] = s2; }
; #pragma unroll
;         for (int rr = 0; rr < 2; ++rr) { const int row = row0 + rr * NGW; if (row >= NTOK) break;
;             const int s = row < NP ? (row >> 12) : 16; const float* md = mod + s * 3072;
;             const float rstd = rsqrtf(wave_sum(ss[rr]) * (1.f / DM) + EPS);
; #pragma unroll
;             for (int jj = 0; jj < 2; ++jj) { const int c = 8 * lane + 512 * jj; f32x4 hv[2];
; #pragma unroll
;                 for (int e = 0; e < 2; ++e) { const f32x4 gn = *(const f32x4*)(P.norm_gain + c + 4 * e), sh = *(const f32x4*)(md + c + 4 * e), scv = *(const f32x4*)(md + 1024 + c + 4 * e);
;                     hv[e] = (v[rr][2 * jj + e] * rstd * gn) * (scv + 1.f) + sh; }
	v_pk_mul_f32 v[214:215], v[100:101], v[100:101]
	v_pk_mul_f32 v[222:223], v[116:117], v[116:117]
	v_pk_fma_f32 v[214:215], v[102:103], v[102:103], v[214:215]
	v_pk_fma_f32 v[222:223], v[118:119], v[118:119], v[222:223]
	v_pk_fma_f32 v[214:215], v[104:105], v[104:105], v[214:215]
	v_pk_fma_f32 v[222:223], v[120:121], v[120:121], v[222:223]
	v_pk_fma_f32 v[214:215], v[106:107], v[106:107], v[214:215]
	v_pk_fma_f32 v[222:223], v[122:123], v[122:123], v[222:223]
	v_pk_fma_f32 v[214:215], v[108:109], v[108:109], v[214:215]
	v_pk_fma_f32 v[222:223], v[124:125], v[124:125], v[222:223]
	v_pk_fma_f32 v[214:215], v[110:111], v[110:111], v[214:215]
	v_pk_fma_f32 v[222:223], v[126:127], v[126:127], v[222:223]
	v_pk_fma_f32 v[214:215], v[112:113], v[112:113], v[214:215]
	v_pk_fma_f32 v[222:223], v[128:129], v[128:129], v[222:223]
	v_pk_fma_f32 v[214:215], v[114:115], v[114:115], v[214:215]
	v_pk_fma_f32 v[222:223], v[130:131], v[130:131], v[222:223]
	v_add_f32_e32 v216, v214, v215
	v_add_f32_e32 v224, v222, v223
	v_pk_add_f32 v[20:21], v[148:149], 1.0 op_sel_hi:[1,0]
	v_pk_add_f32 v[22:23], v[150:151], 1.0 op_sel_hi:[1,0]
	v_add_f32_dpp v217, v216, v216 quad_perm:[1,0,3,2] row_mask:0xf bank_mask:0xf
	v_add_f32_dpp v225, v224, v224 quad_perm:[1,0,3,2] row_mask:0xf bank_mask:0xf
	v_pk_add_f32 v[24:25], v[152:153], 1.0 op_sel_hi:[1,0]
	v_pk_add_f32 v[26:27], v[154:155], 1.0 op_sel_hi:[1,0]
	v_add_f32_dpp v218, v217, v217 quad_perm:[2,3,0,1] row_mask:0xf bank_mask:0xf
	v_add_f32_dpp v226, v225, v225 quad_perm:[2,3,0,1] row_mask:0xf bank_mask:0xf
	v_pk_add_f32 v[28:29], v[156:157], 1.0 op_sel_hi:[1,0]
	v_pk_add_f32 v[30:31], v[158:159], 1.0 op_sel_hi:[1,0]
	v_add_f32_dpp v217, v218, v218 row_half_mirror row_mask:0xf bank_mask:0xf
	v_add_f32_dpp v225, v226, v226 row_half_mirror row_mask:0xf bank_mask:0xf
	v_pk_add_f32 v[32:33], v[160:161], 1.0 op_sel_hi:[1,0]
	v_pk_add_f32 v[34:35], v[162:163], 1.0 op_sel_hi:[1,0]
	v_add_f32_dpp v218, v217, v217 row_mirror row_mask:0xf bank_mask:0xf
	v_add_f32_dpp v226, v225, v225 row_mirror row_mask:0xf bank_mask:0xf
	s_nop 0
	s_nop 0
	v_mov_b32_e32 v219, v218
	v_mov_b32_e32 v227, v226
	s_nop 0
	s_nop 0
	v_permlane16_swap_b32_e32 v218, v219
	v_permlane16_swap_b32_e32 v226, v227
	v_add_f32_e32 v218, v218, v219
	v_add_f32_e32 v226, v226, v227
	v_mov_b32_e32 v219, v218
	v_mov_b32_e32 v227, v226
	s_nop 0
	s_nop 0
	v_permlane32_swap_b32_e32 v218, v219
	v_permlane32_swap_b32_e32 v226, v227
	v_add_f32_e32 v218, v218, v219
	v_add_f32_e32 v226, v226, v227
	v_fmamk_f32 v220, v218, 0x3a800000, v3
	v_fmamk_f32 v228, v226, 0x3a800000, v3
	v_rsq_f32_e32 v220, v220
	v_rsq_f32_e32 v228, v228
	s_nop 0
	v_pk_mul_f32 v[164:165], v[100:101], v[220:221] op_sel_hi:[1,0]
	v_pk_mul_f32 v[166:167], v[102:103], v[220:221] op_sel_hi:[1,0]
	v_pk_mul_f32 v[168:169], v[104:105], v[220:221] op_sel_hi:[1,0]
	v_pk_mul_f32 v[170:171], v[106:107], v[220:221] op_sel_hi:[1,0]
	v_pk_mul_f32 v[172:173], v[108:109], v[220:221] op_sel_hi:[1,0]
	v_pk_mul_f32 v[174:175], v[110:111], v[220:221] op_sel_hi:[1,0]
	v_pk_mul_f32 v[176:177], v[112:113], v[220:221] op_sel_hi:[1,0]
	v_pk_mul_f32 v[178:179], v[114:115], v[220:221] op_sel_hi:[1,0]
	v_pk_mul_f32 v[164:165], v[4:5], v[164:165]
	v_pk_mul_f32 v[166:167], v[6:7], v[166:167]
	v_pk_mul_f32 v[168:169], v[8:9], v[168:169]
	v_pk_mul_f32 v[170:171], v[10:11], v[170:171]
	v_pk_mul_f32 v[172:173], v[12:13], v[172:173]
	v_pk_mul_f32 v[174:175], v[14:15], v[174:175]
	v_pk_mul_f32 v[176:177], v[16:17], v[176:177]
	v_pk_mul_f32 v[178:179], v[18:19], v[178:179]
	v_pk_fma_f32 v[164:165], v[20:21], v[164:165], v[132:133]
	v_pk_fma_f32 v[166:167], v[22:23], v[166:167], v[134:135]
	v_pk_fma_f32 v[168:169], v[24:25], v[168:169], v[136:137]
	v_pk_fma_f32 v[170:171], v[26:27], v[170:171], v[138:139]
	v_pk_fma_f32 v[172:173], v[28:29], v[172:173], v[140:141]
	v_pk_fma_f32 v[174:175], v[30:31], v[174:175], v[142:143]
	v_pk_fma_f32 v[176:177], v[32:33], v[176:177], v[144:145]
	v_pk_fma_f32 v[178:179], v[34:35], v[178:179], v[146:147]
	v_cvt_pk_bf16_f32 v198, v164, v165
	v_cvt_pk_bf16_f32 v199, v166, v167
	v_cvt_pk_bf16_f32 v200, v168, v169
	v_cvt_pk_bf16_f32 v201, v170, v171
	v_cvt_pk_bf16_f32 v202, v172, v173
	v_cvt_pk_bf16_f32 v203, v174, v175
	v_cvt_pk_bf16_f32 v204, v176, v177
	v_cvt_pk_bf16_f32 v205, v178, v179
	v_pk_mul_f32 v[182:183], v[116:117], v[228:229] op_sel_hi:[1,0]
	v_pk_mul_f32 v[184:185], v[118:119], v[228:229] op_sel_hi:[1,0]
	v_pk_mul_f32 v[186:187], v[120:121], v[228:229] op_sel_hi:[1,0]
	v_pk_mul_f32 v[188:189], v[122:123], v[228:229] op_sel_hi:[1,0]
	v_pk_mul_f32 v[190:191], v[124:125], v[228:229] op_sel_hi:[1,0]
	v_pk_mul_f32 v[192:193], v[126:127], v[228:229] op_sel_hi:[1,0]
	v_pk_mul_f32 v[194:195], v[128:129], v[228:229] op_sel_hi:[1,0]
	v_pk_mul_f32 v[196:197], v[130:131], v[228:229] op_sel_hi:[1,0]
	v_pk_mul_f32 v[182:183], v[4:5], v[182:183]
	v_pk_mul_f32 v[184:185], v[6:7], v[184:185]
	v_pk_mul_f32 v[186:187], v[8:9], v[186:187]
	v_pk_mul_f32 v[188:189], v[10:11], v[188:189]
	v_pk_mul_f32 v[190:191], v[12:13], v[190:191]
	v_pk_mul_f32 v[192:193], v[14:15], v[192:193]
	v_pk_mul_f32 v[194:195], v[16:17], v[194:195]
	v_pk_mul_f32 v[196:197], v[18:19], v[196:197]
	v_pk_fma_f32 v[182:183], v[20:21], v[182:183], v[132:133]
	v_pk_fma_f32 v[184:185], v[22:23], v[184:185], v[134:135]
	v_pk_fma_f32 v[186:187], v[24:25], v[186:187], v[136:137]
	v_pk_fma_f32 v[188:189], v[26:27], v[188:189], v[138:139]
	v_pk_fma_f32 v[190:191], v[28:29], v[190:191], v[140:141]
	v_pk_fma_f32 v[192:193], v[30:31], v[192:193], v[142:143]
	v_pk_fma_f32 v[194:195], v[32:33], v[194:195], v[144:145]
	v_pk_fma_f32 v[196:197], v[34:35], v[196:197], v[146:147]
; __device__ __forceinline__ unsigned cvt_pk_bf16(float lo, float hi) { unsigned r; asm volatile("v_cvt_pk_bf16_f32 %0, %1, %2" : "=v"(r) : "v"(lo), "v"(hi)); return r; }
; #define P0B_LOAD(dst_, r0_) do { _Pragma("unroll") for (int rr = 0; rr < 2; ++rr) { const int row = min((r0_) + rr * NGW, NTOK - 1); \
;             const float* xr = row < NP ? P.xp + (size_t)row * DM : P.xs + (size_t)(row - NP) * DM; \
;             _Pragma("unroll") for (int j = 0; j < 4; ++j) dst_[rr][j] = *(const f32x4*)(xr + 8 * lane + 512 * (j >> 1) + 4 * (j & 1)); } } while (0)
; __device__ __forceinline__ void phase0b(const Params& P, int lane, int wave, int bid, int G) {
;     ...
;     P0B_LOAD(v, gw);
;     for (int row0 = gw; row0 < NTOK; row0 += 2 * NGW) {
;         P0B_LOAD(vn, row0 + 2 * NGW);
;         asm volatile("" ::: "memory");
;         float ss[2];
; #pragma unroll
;         for (int rr = 0; rr < 2; ++rr) { float s2 = 0.f;
; #pragma unroll
;             for (int j = 0; j < 4; ++j) s2 += (v[rr][j].x * v[rr][j].x + v[rr][j].y * v[rr][j].y) + (v[rr][j].z * v[rr][j].z + v[rr][j].w * v[rr][j].w);
;             ss[rr] = s2; }
; #pragma unroll
;         for (int rr = 0; rr < 2; ++rr) { const int row = row0 + rr * NGW; if (row >= NTOK) break;
;             const int s = row < NP ? (row >> 12) : 16; const float* md = mod + s * 3072;
;             const float rstd = rsqrtf(wave_sum(ss[rr]) * (1.f / DM) + EPS);
; #pragma unroll
;             for (int jj = 0; jj < 2; ++jj) { const int c = 8 * lane + 512 * jj; f32x4 hv[2];
; #pragma unroll
;                 for (int e = 0; e < 2; ++e) { const f32x4 gn = *(const f32x4*)(P.norm_gain + c + 4 * e), sh = *(const f32x4*)(md + c + 4 * e), scv = *(const f32x4*)(md + 1024 + c + 4 * e);
;                     hv[e] = (v[rr][2 * jj + e] * rstd * gn) * (scv + 1.f) + sh; }
;                 u32x4 o; o.x = cvt_pk_bf16(hv[0].x, hv[0].y); o.y = cvt_pk_bf16(hv[0].z, hv[0].w); o.z = cvt_pk_bf16(hv[1].x, hv[1].y); o.w = cvt_pk_bf16(hv[1].z, hv[1].w);
;                 *(u32x4*)(H + (size_t)row * DM + c) = o; } }
	v_cvt_pk_bf16_f32 v206, v182, v183
	v_cvt_pk_bf16_f32 v207, v184, v185
	v_cvt_pk_bf16_f32 v208, v186, v187
	v_cvt_pk_bf16_f32 v209, v188, v189
	v_cvt_pk_bf16_f32 v210, v190, v191
	v_cvt_pk_bf16_f32 v211, v192, v193
	v_cvt_pk_bf16_f32 v212, v194, v195
	v_cvt_pk_bf16_f32 v213, v196, v197
	global_store_dwordx4 v2, v[198:201], s[10:11]
	global_store_dwordx4 v2, v[202:205], s[10:11] offset:1024
	global_store_dwordx4 v2, v[206:209], s[12:13]
	global_store_dwordx4 v2, v[210:213], s[12:13] offset:1024
	s_add_u32 s10, s10, 0x800000
	s_addc_u32 s11, s11, 0
	s_add_u32 s12, s12, 0x800000
	s_addc_u32 s13, s13, 0
	s_add_i32 s18, s18, 1
	global_load_dwordx4 v[100:103], v1, s[4:5] offset:0
	global_load_dwordx4 v[104:107], v1, s[4:5] offset:16
	global_load_dwordx4 v[108:111], v1, s[4:5] offset:2048
	global_load_dwordx4 v[112:115], v1, s[4:5] offset:2064
	global_load_dwordx4 v[116:119], v1, s[6:7] offset:0
	global_load_dwordx4 v[120:123], v1, s[6:7] offset:16
	global_load_dwordx4 v[124:127], v1, s[6:7] offset:2048
	global_load_dwordx4 v[128:131], v1, s[6:7] offset:2064
	global_load_dwordx4 v[132:135], v1, s[14:15] offset:0
	global_load_dwordx4 v[136:139], v1, s[14:15] offset:16
	global_load_dwordx4 v[140:143], v1, s[14:15] offset:2048
	global_load_dwordx4 v[144:147], v1, s[14:15] offset:2064
	global_load_dwordx4 v[148:151], v1, s[16:17] offset:0
	global_load_dwordx4 v[152:155], v1, s[16:17] offset:16
	global_load_dwordx4 v[156:159], v1, s[16:17] offset:2048
	global_load_dwordx4 v[160:163], v1, s[16:17] offset:2064
	s_add_u32 s4, s4, 0x1000000
	s_addc_u32 s5, s5, 0
	s_cmp_eq_u32 s18, 14
	s_cselect_b32 s4, s20, s4
	s_cselect_b32 s5, s21, s5
	s_add_u32 s6, s4, 0x800000
	s_addc_u32 s7, s5, 0
	s_add_i32 vcc_lo, s18, 2
	s_min_u32 vcc_lo, vcc_lo, 16
	s_mul_i32 vcc_lo, vcc_lo, 0x3000
	s_add_u32 s14, s24, vcc_lo
	s_addc_u32 s15, s19, 0
	s_add_u32 s16, s14, 0x1000
	s_addc_u32 s17, s15, 0
	s_waitcnt vmcnt(20)
	v_pk_mul_f32 v[214:215], v[36:37], v[36:37]
	v_pk_mul_f32 v[222:223], v[52:53], v[52:53]
	v_pk_fma_f32 v[214:215], v[38:39], v[38:39], v[214:215]
	v_pk_fma_f32 v[222:223], v[54:55], v[54:55], v[222:223]
	v_pk_fma_f32 v[214:215], v[40:41], v[40:41], v[214:215]
	v_pk_fma_f32 v[222:223], v[56:57], v[56:57], v[222:223]
	v_pk_fma_f32 v[214:215], v[42:43], v[42:43], v[214:215]
	v_pk_fma_f32 v[222:223], v[58:59], v[58:59], v[222:223]
	v_pk_fma_f32 v[214:215], v[44:45], v[44:45], v[214:215]
	v_pk_fma_f32 v[222:223], v[60:61], v[60:61], v[222:223]
	v_pk_fma_f32 v[214:215], v[46:47], v[46:47], v[214:215]
	v_pk_fma_f32 v[222:223], v[62:63], v[62:63], v[222:223]
	v_pk_fma_f32 v[214:215], v[48:49], v[48:49], v[214:215]
	v_pk_fma_f32 v[222:223], v[64:65], v[64:65], v[222:223]
	v_pk_fma_f32 v[214:215], v[50:51], v[50:51], v[214:215]
	v_pk_fma_f32 v[222:223], v[66:67], v[66:67], v[222:223]
	v_add_f32_e32 v216, v214, v215
	v_add_f32_e32 v224, v222, v223
	v_pk_add_f32 v[20:21], v[84:85], 1.0 op_sel_hi:[1,0]
	v_pk_add_f32 v[22:23], v[86:87], 1.0 op_sel_hi:[1,0]
	v_add_f32_dpp v217, v216, v216 quad_perm:[1,0,3,2] row_mask:0xf bank_mask:0xf
	v_add_f32_dpp v225, v224, v224 quad_perm:[1,0,3,2] row_mask:0xf bank_mask:0xf
	v_pk_add_f32 v[24:25], v[88:89], 1.0 op_sel_hi:[1,0]
	v_pk_add_f32 v[26:27], v[90:91], 1.0 op_sel_hi:[1,0]
	v_add_f32_dpp v218, v217, v217 quad_perm:[2,3,0,1] row_mask:0xf bank_mask:0xf
	v_add_f32_dpp v226, v225, v225 quad_perm:[2,3,0,1] row_mask:0xf bank_mask:0xf
	v_pk_add_f32 v[28:29], v[92:93], 1.0 op_sel_hi:[1,0]
	v_pk_add_f32 v[30:31], v[94:95], 1.0 op_sel_hi:[1,0]
	v_add_f32_dpp v217, v218, v218 row_half_mirror row_mask:0xf bank_mask:0xf
	v_add_f32_dpp v225, v226, v226 row_half_mirror row_mask:0xf bank_mask:0xf
	v_pk_add_f32 v[32:33], v[96:97], 1.0 op_sel_hi:[1,0]
	v_pk_add_f32 v[34:35], v[98:99], 1.0 op_sel_hi:[1,0]
	v_add_f32_dpp v218, v217, v217 row_mirror row_mask:0xf bank_mask:0xf
	v_add_f32_dpp v226, v225, v225 row_mirror row_mask:0xf bank_mask:0xf
	s_nop 0
	s_nop 0
	v_mov_b32_e32 v219, v218
	v_mov_b32_e32 v227, v226
	s_nop 0
	s_nop 0
	v_permlane16_swap_b32_e32 v218, v219
	v_permlane16_swap_b32_e32 v226, v227
	v_add_f32_e32 v218, v218, v219
	v_add_f32_e32 v226, v226, v227
	v_mov_b32_e32 v219, v218
	v_mov_b32_e32 v227, v226
	s_nop 0
	s_nop 0
	v_permlane32_swap_b32_e32 v218, v219
	v_permlane32_swap_b32_e32 v226, v227
	v_add_f32_e32 v218, v218, v219
	v_add_f32_e32 v226, v226, v227
	v_fmamk_f32 v220, v218, 0x3a800000, v3
	v_fmamk_f32 v228, v226, 0x3a800000, v3
	v_rsq_f32_e32 v220, v220
	v_rsq_f32_e32 v228, v228
	s_nop 0
	v_pk_mul_f32 v[164:165], v[36:37], v[220:221] op_sel_hi:[1,0]
	v_pk_mul_f32 v[166:167], v[38:39], v[220:221] op_sel_hi:[1,0]
	v_pk_mul_f32 v[168:169], v[40:41], v[220:221] op_sel_hi:[1,0]
	v_pk_mul_f32 v[170:171], v[42:43], v[220:221] op_sel_hi:[1,0]
	v_pk_mul_f32 v[172:173], v[44:45], v[220:221] op_sel_hi:[1,0]
	v_pk_mul_f32 v[174:175], v[46:47], v[220:221] op_sel_hi:[1,0]
	v_pk_mul_f32 v[176:177], v[48:49], v[220:221] op_sel_hi:[1,0]
	v_pk_mul_f32 v[178:179], v[50:51], v[220:221] op_sel_hi:[1,0]
	v_pk_mul_f32 v[164:165], v[4:5], v[164:165]
	v_pk_mul_f32 v[166:167], v[6:7], v[166:167]
	v_pk_mul_f32 v[168:169], v[8:9], v[168:169]
	v_pk_mul_f32 v[170:171], v[10:11], v[170:171]
	v_pk_mul_f32 v[172:173], v[12:13], v[172:173]
	v_pk_mul_f32 v[174:175], v[14:15], v[174:175]
	v_pk_mul_f32 v[176:177], v[16:17], v[176:177]
	v_pk_mul_f32 v[178:179], v[18:19], v[178:179]
	v_pk_fma_f32 v[164:165], v[20:21], v[164:165], v[68:69]
	v_pk_fma_f32 v[166:167], v[22:23], v[166:167], v[70:71]
	v_pk_fma_f32 v[168:169], v[24:25], v[168:169], v[72:73]
	v_pk_fma_f32 v[170:171], v[26:27], v[170:171], v[74:75]
	v_pk_fma_f32 v[172:173], v[28:29], v[172:173], v[76:77]
; __device__ __forceinline__ unsigned cvt_pk_bf16(float lo, float hi) { unsigned r; asm volatile("v_cvt_pk_bf16_f32 %0, %1, %2" : "=v"(r) : "v"(lo), "v"(hi)); return r; }
; #define P0B_LOAD(dst_, r0_) do { _Pragma("unroll") for (int rr = 0; rr < 2; ++rr) { const int row = min((r0_) + rr * NGW, NTOK - 1); \
;             const float* xr = row < NP ? P.xp + (size_t)row * DM : P.xs + (size_t)(row - NP) * DM; \
;             _Pragma("unroll") for (int j = 0; j < 4; ++j) dst_[rr][j] = *(const f32x4*)(xr + 8 * lane + 512 * (j >> 1) + 4 * (j & 1)); } } while (0)
; __device__ __forceinline__ void phase0b(const Params& P, int lane, int wave, int bid, int G) {
;     ...
;     for (int row0 = gw; row0 < NTOK; row0 += 2 * NGW) {
;         P0B_LOAD(vn, row0 + 2 * NGW);
;         asm volatile("" ::: "memory");
;         float ss[2];
; #pragma unroll
;         for (int rr = 0; rr < 2; ++rr) { float s2 = 0.f;
; #pragma unroll
;             for (int j = 0; j < 4; ++j) s2 += (v[rr][j].x * v[rr][j].x + v[rr][j].y * v[rr][j].y) + (v[rr][j].z * v[rr][j].z + v[rr][j].w * v[rr][j].w);
;             ss[rr] = s2; }
; #pragma unroll
;         for (int rr = 0; rr < 2; ++rr) { const int row = row0 + rr * NGW; if (row >= NTOK) break;
;             const int s = row < NP ? (row >> 12) : 16; const float* md = mod + s * 3072;
;             const float rstd = rsqrtf(wave_sum(ss[rr]) * (1.f / DM) + EPS);
; #pragma unroll
;             for (int jj = 0; jj < 2; ++jj) { const int c = 8 * lane + 512 * jj; f32x4 hv[2];
; #pragma unroll
;                 for (int e = 0; e < 2; ++e) { const f32x4 gn = *(const f32x4*)(P.norm_gain + c + 4 * e), sh = *(const f32x4*)(md + c + 4 * e), scv = *(const f32x4*)(md + 1024 + c + 4 * e);
;                     hv[e] = (v[rr][2 * jj + e] * rstd * gn) * (scv + 1.f) + sh; }
;                 u32x4 o; o.x = cvt_pk_bf16(hv[0].x, hv[0].y); o.y = cvt_pk_bf16(hv[0].z, hv[0].w); o.z = cvt_pk_bf16(hv[1].x, hv[1].y); o.w = cvt_pk_bf16(hv[1].z, hv[1].w);
;                 *(u32x4*)(H + (size_t)row * DM + c) = o; } }
; #pragma unroll
;         for (int rr = 0; rr < 2; ++rr)
; #pragma unroll
;             for (int j = 0; j < 4; ++j) v[rr][j] = vn[rr][j];
;     }
	v_pk_fma_f32 v[174:175], v[30:31], v[174:175], v[78:79]
	v_pk_fma_f32 v[176:177], v[32:33], v[176:177], v[80:81]
	v_pk_fma_f32 v[178:179], v[34:35], v[178:179], v[82:83]
	v_cvt_pk_bf16_f32 v198, v164, v165
	v_cvt_pk_bf16_f32 v199, v166, v167
	v_cvt_pk_bf16_f32 v200, v168, v169
	v_cvt_pk_bf16_f32 v201, v170, v171
	v_cvt_pk_bf16_f32 v202, v172, v173
	v_cvt_pk_bf16_f32 v203, v174, v175
	v_cvt_pk_bf16_f32 v204, v176, v177
	v_cvt_pk_bf16_f32 v205, v178, v179
	v_pk_mul_f32 v[182:183], v[52:53], v[228:229] op_sel_hi:[1,0]
	v_pk_mul_f32 v[184:185], v[54:55], v[228:229] op_sel_hi:[1,0]
	v_pk_mul_f32 v[186:187], v[56:57], v[228:229] op_sel_hi:[1,0]
	v_pk_mul_f32 v[188:189], v[58:59], v[228:229] op_sel_hi:[1,0]
	v_pk_mul_f32 v[190:191], v[60:61], v[228:229] op_sel_hi:[1,0]
	v_pk_mul_f32 v[192:193], v[62:63], v[228:229] op_sel_hi:[1,0]
	v_pk_mul_f32 v[194:195], v[64:65], v[228:229] op_sel_hi:[1,0]
	v_pk_mul_f32 v[196:197], v[66:67], v[228:229] op_sel_hi:[1,0]
	v_pk_mul_f32 v[182:183], v[4:5], v[182:183]
	v_pk_mul_f32 v[184:185], v[6:7], v[184:185]
	v_pk_mul_f32 v[186:187], v[8:9], v[186:187]
	v_pk_mul_f32 v[188:189], v[10:11], v[188:189]
	v_pk_mul_f32 v[190:191], v[12:13], v[190:191]
	v_pk_mul_f32 v[192:193], v[14:15], v[192:193]
	v_pk_mul_f32 v[194:195], v[16:17], v[194:195]
	v_pk_mul_f32 v[196:197], v[18:19], v[196:197]
	v_pk_fma_f32 v[182:183], v[20:21], v[182:183], v[68:69]
	v_pk_fma_f32 v[184:185], v[22:23], v[184:185], v[70:71]
	v_pk_fma_f32 v[186:187], v[24:25], v[186:187], v[72:73]
	v_pk_fma_f32 v[188:189], v[26:27], v[188:189], v[74:75]
	v_pk_fma_f32 v[190:191], v[28:29], v[190:191], v[76:77]
	v_pk_fma_f32 v[192:193], v[30:31], v[192:193], v[78:79]
	v_pk_fma_f32 v[194:195], v[32:33], v[194:195], v[80:81]
	v_pk_fma_f32 v[196:197], v[34:35], v[196:197], v[82:83]
	v_cvt_pk_bf16_f32 v206, v182, v183
	v_cvt_pk_bf16_f32 v207, v184, v185
	v_cvt_pk_bf16_f32 v208, v186, v187
	v_cvt_pk_bf16_f32 v209, v188, v189
	v_cvt_pk_bf16_f32 v210, v190, v191
	v_cvt_pk_bf16_f32 v211, v192, v193
	v_cvt_pk_bf16_f32 v212, v194, v195
	v_cvt_pk_bf16_f32 v213, v196, v197
	global_store_dwordx4 v2, v[198:201], s[10:11]
	global_store_dwordx4 v2, v[202:205], s[10:11] offset:1024
	global_store_dwordx4 v2, v[206:209], s[12:13]
	global_store_dwordx4 v2, v[210:213], s[12:13] offset:1024
	s_add_u32 s10, s10, 0x800000
	s_addc_u32 s11, s11, 0
	s_add_u32 s12, s12, 0x800000
	s_addc_u32 s13, s13, 0
	s_add_i32 s18, s18, 1
	s_cmp_lt_u32 s18, 19
	s_cbranch_scc1 .Lp0b_loop
	s_waitcnt vmcnt(4)
	v_pk_mul_f32 v[214:215], v[100:101], v[100:101]
	v_pk_mul_f32 v[222:223], v[116:117], v[116:117]
	v_pk_fma_f32 v[214:215], v[102:103], v[102:103], v[214:215]
	v_pk_fma_f32 v[222:223], v[118:119], v[118:119], v[222:223]
	v_pk_fma_f32 v[214:215], v[104:105], v[104:105], v[214:215]
	v_pk_fma_f32 v[222:223], v[120:121], v[120:121], v[222:223]
	v_pk_fma_f32 v[214:215], v[106:107], v[106:107], v[214:215]
	v_pk_fma_f32 v[222:223], v[122:123], v[122:123], v[222:223]
	v_pk_fma_f32 v[214:215], v[108:109], v[108:109], v[214:215]
	v_pk_fma_f32 v[222:223], v[124:125], v[124:125], v[222:223]
	v_pk_fma_f32 v[214:215], v[110:111], v[110:111], v[214:215]
	v_pk_fma_f32 v[222:223], v[126:127], v[126:127], v[222:223]
	v_pk_fma_f32 v[214:215], v[112:113], v[112:113], v[214:215]
	v_pk_fma_f32 v[222:223], v[128:129], v[128:129], v[222:223]
	v_pk_fma_f32 v[214:215], v[114:115], v[114:115], v[214:215]
	v_pk_fma_f32 v[222:223], v[130:131], v[130:131], v[222:223]
	v_add_f32_e32 v216, v214, v215
	v_add_f32_e32 v224, v222, v223
	v_pk_add_f32 v[20:21], v[148:149], 1.0 op_sel_hi:[1,0]
	v_pk_add_f32 v[22:23], v[150:151], 1.0 op_sel_hi:[1,0]
	v_add_f32_dpp v217, v216, v216 quad_perm:[1,0,3,2] row_mask:0xf bank_mask:0xf
	v_add_f32_dpp v225, v224, v224 quad_perm:[1,0,3,2] row_mask:0xf bank_mask:0xf
	v_pk_add_f32 v[24:25], v[152:153], 1.0 op_sel_hi:[1,0]
	v_pk_add_f32 v[26:27], v[154:155], 1.0 op_sel_hi:[1,0]
	v_add_f32_dpp v218, v217, v217 quad_perm:[2,3,0,1] row_mask:0xf bank_mask:0xf
	v_add_f32_dpp v226, v225, v225 quad_perm:[2,3,0,1] row_mask:0xf bank_mask:0xf
	v_pk_add_f32 v[28:29], v[156:157], 1.0 op_sel_hi:[1,0]
	v_pk_add_f32 v[30:31], v[158:159], 1.0 op_sel_hi:[1,0]
	v_add_f32_dpp v217, v218, v218 row_half_mirror row_mask:0xf bank_mask:0xf
	v_add_f32_dpp v225, v226, v226 row_half_mirror row_mask:0xf bank_mask:0xf
	v_pk_add_f32 v[32:33], v[160:161], 1.0 op_sel_hi:[1,0]
	v_pk_add_f32 v[34:35], v[162:163], 1.0 op_sel_hi:[1,0]
	v_add_f32_dpp v218, v217, v217 row_mirror row_mask:0xf bank_mask:0xf
	v_add_f32_dpp v226, v225, v225 row_mirror row_mask:0xf bank_mask:0xf
	s_nop 0
	s_nop 0
	v_mov_b32_e32 v219, v218
	v_mov_b32_e32 v227, v226
	s_nop 0
	s_nop 0
	v_permlane16_swap_b32_e32 v218, v219
	v_permlane16_swap_b32_e32 v226, v227
	v_add_f32_e32 v218, v218, v219
	v_add_f32_e32 v226, v226, v227
	v_mov_b32_e32 v219, v218
	v_mov_b32_e32 v227, v226
	s_nop 0
	s_nop 0
	v_permlane32_swap_b32_e32 v218, v219
	v_permlane32_swap_b32_e32 v226, v227
	v_add_f32_e32 v218, v218, v219
	v_add_f32_e32 v226, v226, v227
	v_fmamk_f32 v220, v218, 0x3a800000, v3
	v_fmamk_f32 v228, v226, 0x3a800000, v3
	v_rsq_f32_e32 v220, v220
	v_rsq_f32_e32 v228, v228
	s_nop 0
	v_pk_mul_f32 v[164:165], v[100:101], v[220:221] op_sel_hi:[1,0]
	v_pk_mul_f32 v[166:167], v[102:103], v[220:221] op_sel_hi:[1,0]
	v_pk_mul_f32 v[168:169], v[104:105], v[220:221] op_sel_hi:[1,0]
	v_pk_mul_f32 v[170:171], v[106:107], v[220:221] op_sel_hi:[1,0]
; __device__ __forceinline__ unsigned cvt_pk_bf16(float lo, float hi) { unsigned r; asm volatile("v_cvt_pk_bf16_f32 %0, %1, %2" : "=v"(r) : "v"(lo), "v"(hi)); return r; }
; #define P0B_LOAD(dst_, r0_) do { _Pragma("unroll") for (int rr = 0; rr < 2; ++rr) { const int row = min((r0_) + rr * NGW, NTOK - 1); \
;             const float* xr = row < NP ? P.xp + (size_t)row * DM : P.xs + (size_t)(row - NP) * DM; \
;             _Pragma("unroll") for (int j = 0; j < 4; ++j) dst_[rr][j] = *(const f32x4*)(xr + 8 * lane + 512 * (j >> 1) + 4 * (j & 1)); } } while (0)
; __device__ __forceinline__ void phase0b(const Params& P, int lane, int wave, int bid, int G) {
;     const float* mod = (const float*)(P.ws + OFF_MOD); bf16_t* H = (bf16_t*)(P.ws + OFF_H);
;     const int gw = bid * 8 + wave, NGW = G * 8;
;     f32x4 v[2][4], vn[2][4];
;     ...
;     P0B_LOAD(v, gw);
;     for (int row0 = gw; row0 < NTOK; row0 += 2 * NGW) {
;         P0B_LOAD(vn, row0 + 2 * NGW);
;     ...
;             for (int jj = 0; jj < 2; ++jj) { const int c = 8 * lane + 512 * jj; f32x4 hv[2];
; #pragma unroll
;                 for (int e = 0; e < 2; ++e) { const f32x4 gn = *(const f32x4*)(P.norm_gain + c + 4 * e), sh = *(const f32x4*)(md + c + 4 * e), scv = *(const f32x4*)(md + 1024 + c + 4 * e);
;                     hv[e] = (v[rr][2 * jj + e] * rstd * gn) * (scv + 1.f) + sh; }
;                 u32x4 o; o.x = cvt_pk_bf16(hv[0].x, hv[0].y); o.y = cvt_pk_bf16(hv[0].z, hv[0].w); o.z = cvt_pk_bf16(hv[1].x, hv[1].y); o.w = cvt_pk_bf16(hv[1].z, hv[1].w);
;                 *(u32x4*)(H + (size_t)row * DM + c) = o; } }
	v_pk_mul_f32 v[172:173], v[108:109], v[220:221] op_sel_hi:[1,0]
	v_pk_mul_f32 v[174:175], v[110:111], v[220:221] op_sel_hi:[1,0]
	v_pk_mul_f32 v[176:177], v[112:113], v[220:221] op_sel_hi:[1,0]
	v_pk_mul_f32 v[178:179], v[114:115], v[220:221] op_sel_hi:[1,0]
	v_pk_mul_f32 v[164:165], v[4:5], v[164:165]
	v_pk_mul_f32 v[166:167], v[6:7], v[166:167]
	v_pk_mul_f32 v[168:169], v[8:9], v[168:169]
	v_pk_mul_f32 v[170:171], v[10:11], v[170:171]
	v_pk_mul_f32 v[172:173], v[12:13], v[172:173]
	v_pk_mul_f32 v[174:175], v[14:15], v[174:175]
	v_pk_mul_f32 v[176:177], v[16:17], v[176:177]
	v_pk_mul_f32 v[178:179], v[18:19], v[178:179]
	v_pk_fma_f32 v[164:165], v[20:21], v[164:165], v[132:133]
	v_pk_fma_f32 v[166:167], v[22:23], v[166:167], v[134:135]
	v_pk_fma_f32 v[168:169], v[24:25], v[168:169], v[136:137]
	v_pk_fma_f32 v[170:171], v[26:27], v[170:171], v[138:139]
	v_pk_fma_f32 v[172:173], v[28:29], v[172:173], v[140:141]
	v_pk_fma_f32 v[174:175], v[30:31], v[174:175], v[142:143]
	v_pk_fma_f32 v[176:177], v[32:33], v[176:177], v[144:145]
	v_pk_fma_f32 v[178:179], v[34:35], v[178:179], v[146:147]
	v_cvt_pk_bf16_f32 v198, v164, v165
	v_cvt_pk_bf16_f32 v199, v166, v167
	v_cvt_pk_bf16_f32 v200, v168, v169
	v_cvt_pk_bf16_f32 v201, v170, v171
	v_cvt_pk_bf16_f32 v202, v172, v173
	v_cvt_pk_bf16_f32 v203, v174, v175
	v_cvt_pk_bf16_f32 v204, v176, v177
	v_cvt_pk_bf16_f32 v205, v178, v179
	v_pk_mul_f32 v[182:183], v[116:117], v[228:229] op_sel_hi:[1,0]
	v_pk_mul_f32 v[184:185], v[118:119], v[228:229] op_sel_hi:[1,0]
	v_pk_mul_f32 v[186:187], v[120:121], v[228:229] op_sel_hi:[1,0]
	v_pk_mul_f32 v[188:189], v[122:123], v[228:229] op_sel_hi:[1,0]
	v_pk_mul_f32 v[190:191], v[124:125], v[228:229] op_sel_hi:[1,0]
	v_pk_mul_f32 v[192:193], v[126:127], v[228:229] op_sel_hi:[1,0]
	v_pk_mul_f32 v[194:195], v[128:129], v[228:229] op_sel_hi:[1,0]
	v_pk_mul_f32 v[196:197], v[130:131], v[228:229] op_sel_hi:[1,0]
	v_pk_mul_f32 v[182:183], v[4:5], v[182:183]
	v_pk_mul_f32 v[184:185], v[6:7], v[184:185]
	v_pk_mul_f32 v[186:187], v[8:9], v[186:187]
	v_pk_mul_f32 v[188:189], v[10:11], v[188:189]
	v_pk_mul_f32 v[190:191], v[12:13], v[190:191]
	v_pk_mul_f32 v[192:193], v[14:15], v[192:193]
	v_pk_mul_f32 v[194:195], v[16:17], v[194:195]
	v_pk_mul_f32 v[196:197], v[18:19], v[196:197]
	v_pk_fma_f32 v[182:183], v[20:21], v[182:183], v[132:133]
	v_pk_fma_f32 v[184:185], v[22:23], v[184:185], v[134:135]
	v_pk_fma_f32 v[186:187], v[24:25], v[186:187], v[136:137]
	v_pk_fma_f32 v[188:189], v[26:27], v[188:189], v[138:139]
	v_pk_fma_f32 v[190:191], v[28:29], v[190:191], v[140:141]
	v_pk_fma_f32 v[192:193], v[30:31], v[192:193], v[142:143]
	v_pk_fma_f32 v[194:195], v[32:33], v[194:195], v[144:145]
	v_pk_fma_f32 v[196:197], v[34:35], v[196:197], v[146:147]
	v_cvt_pk_bf16_f32 v206, v182, v183
	v_cvt_pk_bf16_f32 v207, v184, v185
	v_cvt_pk_bf16_f32 v208, v186, v187
	v_cvt_pk_bf16_f32 v209, v188, v189
	v_cvt_pk_bf16_f32 v210, v190, v191
	v_cvt_pk_bf16_f32 v211, v192, v193
	v_cvt_pk_bf16_f32 v212, v194, v195
	v_cvt_pk_bf16_f32 v213, v196, v197
	global_store_dwordx4 v2, v[198:201], s[10:11]
	global_store_dwordx4 v2, v[202:205], s[10:11] offset:1024
	global_store_dwordx4 v2, v[206:209], s[12:13]
	global_store_dwordx4 v2, v[210:213], s[12:13] offset:1024
	s_add_u32 s10, s10, 0x800000
	s_addc_u32 s11, s11, 0
	s_add_u32 s12, s12, 0x800000
	s_addc_u32 s13, s13, 0
	s_add_i32 s18, s18, 1
	s_branch .LBB0_96
.Lp0b_generic:
	s_add_u32 s17, s22, 0x10000
	s_addc_u32 s18, s23, 0
	s_lshl_b32 s5, s3, 3
	s_add_i32 s5, s5, s6
	s_min_i32 s7, s5, 0x13fff
	s_lshl_b32 s4, s3, 4
	s_ashr_i32 s10, s7, 31
	s_add_i32 s12, s7, 0xffff0000
	s_cmp_lt_i32 s5, 0x10000
	s_cselect_b32 s11, s10, 0
	s_cselect_b32 s10, s7, s12
	s_cselect_b32 s5, s37, s39
	s_cselect_b32 s13, s36, s38
	s_lshl_b64 s[10:11], s[10:11], 12
	s_add_u32 s10, s13, s10
	s_addc_u32 s11, s5, s11
	s_ashr_i32 s7, s6, 31
	s_add_i32 s5, s6, 0xffff0000
	s_cmp_lt_i32 s6, 0x10000
	s_cselect_b32 s13, s7, 0
	s_cselect_b32 s12, s6, s5
	s_cselect_b32 s14, s37, s39
	s_cselect_b32 s15, s36, s38
	s_lshl_b64 s[12:13], s[12:13], 12
	s_add_u32 s12, s15, s12
	v_lshlrev_b32_e32 v10, 5, v180
	s_addc_u32 s13, s14, s13
	global_load_dwordx4 v[50:53], v10, s[12:13] offset:2064
	global_load_dwordx4 v[54:57], v10, s[12:13] offset:2048
	global_load_dwordx4 v[58:61], v10, s[12:13] offset:16
	global_load_dwordx4 v[62:65], v10, s[12:13]
	global_load_dwordx4 v[2:5], v10, s[10:11] offset:2064
	global_load_dwordx4 v[6:9], v10, s[10:11] offset:2048
	global_load_dwordx4 v[42:45], v10, s[10:11] offset:16
	global_load_dwordx4 v[46:49], v10, s[10:11]
	s_lshl_b64 s[6:7], s[6:7], 11
	v_mov_b32_e32 v11, 0
	s_add_u32 s6, s22, s6
	v_lshlrev_b32_e32 v66, 3, v180
	v_lshl_add_u64 v[68:69], s[44:45], 0, v[10:11]
	v_lshlrev_b32_e32 v10, 4, v180
	s_addc_u32 s7, s23, s7
	s_ashr_i32 s5, s4, 31
	v_or_b32_e32 v12, 0x200, v66
	v_lshl_add_u64 v[14:15], s[22:23], 0, v[10:11]
	s_mov_b64 s[10:11], 0x2000000
	v_lshl_add_u64 v[10:11], s[6:7], 0, v[10:11]
	s_lshl_b64 s[6:7], s[4:5], 11
	s_add_i32 s5, s2, s3
	s_mul_i32 s19, s3, 24
	v_mbcnt_lo_u32_b32 v1, -1, 0
	v_lshl_add_u64 v[70:71], v[14:15], 0, s[10:11]
	v_lshl_add_u64 v[72:73], v[10:11], 0, s[10:11]
	s_lshl_b32 s5, s5, 3
	s_add_i32 s19, s19, s16
	s_add_i32 s20, s4, s16
	v_mbcnt_hi_u32_b32 v1, -1, v1
	v_mov_b32_e32 v67, 0x358637bd
	s_mov_b32 s21, 0x800000
	v_lshlrev_b32_e32 v74, 2, v12
	s_mov_b32 s24, s97
	s_branch .LBB0_94

; #define PG8_STAGE(bufoff, gbase, voff) do { _Pragma("unroll") for (int _i = 0; _i < 2; ++_i) \
;         __builtin_amdgcn_global_load_lds((const unsigned*)((const char*)(gbase) + (voff)[_i]), (PG8_LAS unsigned*)(lds + (bufoff) + ldsw + _i * 8192), 16, 0, 0); } while (0)
; #define PG8_LDA(dst, b, h) do { _Pragma("unroll") for (int m = 0; m < 4; ++m) _Pragma("unroll") for (int k = 0; k < 2; ++k) dst[m][k] = *(const PG8_LAS bf16x8*)(lds + PG8_SA(b, h) + aoff + m * 2048 + k * 1024); } while (0)
; #define PG8_LDB(dst, b, h) do { _Pragma("unroll") for (int n = 0; n < 2; ++n) _Pragma("unroll") for (int k = 0; k < 2; ++k) dst[n][k] = *(const PG8_LAS bf16x8*)(lds + PG8_SB(b, h) + boff + n * 2048 + k * 1024); } while (0)
; #define PG8_WAIT_V(n) asm volatile("s_waitcnt vmcnt(" #n ")" ::: "memory")
; #define PG8_WAIT_L(n) asm volatile("s_waitcnt lgkmcnt(" #n ")" ::: "memory")
; #define PG8_BAR __builtin_amdgcn_s_barrier()
; #define PG8_SCHED __builtin_amdgcn_sched_barrier(0)
; template <class Epi, class Sched, bool ALIGN_EPI = false, bool SP2 = false>
; __device__ __forceinline__ void gemm_phase(PG8_LAS unsigned char* lds, const Gemm g, const Sched& S, const Epi& E) {
;     ...
;         const bool has_next = S.next(ui + 1, nxt);
;         const char* nA = has_next ? (const char*)g.A + (size_t)nxt.pm * tstep : cA; const char* nB = has_next ? (const char*)g.Bt + (size_t)nxt.pn * tstep : cB;
;         for (int t = 0; t < nt; t += 2) {
;             const bool last = (t == nt - 2);
;             const char* a1 = cA + (size_t)(t + 1) * kstep;
;             const char* a2 = last ? nA : cA + (size_t)(t + 2) * kstep; const char* b2 = last ? nB : cB + (size_t)(t + 2) * kstep;
;             const char* a3 = a2 + kstep; const char* b3 = b2 + kstep;
;             if (last && has_next) S.a_ready(nxt);
;             if constexpr (SP2) {
;             PG8_LDB(B0, 0, 0); PG8_LDB(B1, 0, 1); PG8_SCHED; PG8_LDA(At, 0, 0); PG8_STAGE(PG8_SA(1, 1), a1 + hstep, voffA);
;             PG8_WAIT_V(8); PG8_WAIT_L(0); PG8_BAR; PG8_MMA(0, 0, At, B0); PG8_MMA(0, 1, At, B1); PG8_BAR; PG8_SCHED;
;     ...
; #pragma unroll
;         for (int a = 0; a < 2; ++a)
; #pragma unroll
;             for (int b = 0; b < 2; ++b)
; #pragma unroll
;                 for (int m = 0; m < 4; ++m)
; #pragma unroll
;                     for (int n = 0; n < 2; ++n) acc[a][b][m][n] = (f32x4){0.f, 0.f, 0.f, 0.f};
.LBB0_161:
	s_ashr_i32 s41, s40, 31
	s_lshl_b64 s[34:35], s[40:41], 19
	s_add_u32 s42, s68, s34
	s_addc_u32 s43, s69, s35
	s_and_b64 s[34:35], s[0:1], exec
	s_cselect_b32 s5, s43, s49
	s_cselect_b32 s34, s42, s48
	s_ashr_i32 s27, s26, 31
	s_lshl_b64 s[44:45], s[26:27], 19
	s_add_u32 s44, s70, s44
	s_addc_u32 s45, s71, s45
	s_and_b64 s[64:65], s[0:1], exec
	s_cselect_b32 s27, s45, s51
	s_cselect_b32 s35, s44, s50
	s_add_u32 s48, s48, 0x40080
	s_addc_u32 s49, s49, 0
	s_add_u32 s41, s50, 0x100
	v_mov_b32_e32 v2, 0
	s_addc_u32 s92, s51, 0
	s_mov_b32 s93, -2
	v_mov_b32_e32 v3, v2
	s_cmp_lg_u32 s76, 1
	s_cbranch_scc1 .Lp1_peel
	v_mov_b32_e32 v4, v2
	v_mov_b32_e32 v5, v2
	v_mov_b32_e32 v6, v2
	v_mov_b32_e32 v7, v2
	v_mov_b32_e32 v8, v2
	v_mov_b32_e32 v9, v2
	v_mov_b32_e32 v18, v2
	v_mov_b32_e32 v19, v2
	v_mov_b32_e32 v20, v2
	v_mov_b32_e32 v21, v2
	v_mov_b32_e32 v22, v2
	v_mov_b32_e32 v23, v2
	v_mov_b32_e32 v24, v2
	v_mov_b32_e32 v25, v2
	v_mov_b32_e32 v34, v2
	v_mov_b32_e32 v35, v2
	v_mov_b32_e32 v36, v2
	v_mov_b32_e32 v37, v2
	v_mov_b32_e32 v38, v2
	v_mov_b32_e32 v39, v2
	v_mov_b32_e32 v40, v2
	v_mov_b32_e32 v41, v2
	v_mov_b32_e32 v50, v2
	v_mov_b32_e32 v51, v2
	v_mov_b32_e32 v52, v2
	v_mov_b32_e32 v53, v2
	v_mov_b32_e32 v54, v2
	v_mov_b32_e32 v55, v2
	v_mov_b32_e32 v56, v2
	v_mov_b32_e32 v57, v2
	v_mov_b32_e32 v10, v2
	v_mov_b32_e32 v11, v2
	v_mov_b32_e32 v12, v2
	v_mov_b32_e32 v13, v2
	v_mov_b32_e32 v14, v2
	v_mov_b32_e32 v15, v2
	v_mov_b32_e32 v16, v2
	v_mov_b32_e32 v17, v2
	v_mov_b32_e32 v26, v2
	v_mov_b32_e32 v27, v2
	v_mov_b32_e32 v28, v2
	v_mov_b32_e32 v29, v2
	v_mov_b32_e32 v30, v2
	v_mov_b32_e32 v31, v2
	v_mov_b32_e32 v32, v2
	v_mov_b32_e32 v33, v2
	v_mov_b32_e32 v42, v2
	v_mov_b32_e32 v43, v2
	v_mov_b32_e32 v44, v2
	v_mov_b32_e32 v45, v2
	v_mov_b32_e32 v46, v2
	v_mov_b32_e32 v47, v2
	v_mov_b32_e32 v48, v2
	v_mov_b32_e32 v49, v2
	v_mov_b32_e32 v58, v2
	v_mov_b32_e32 v59, v2
	v_mov_b32_e32 v60, v2
	v_mov_b32_e32 v61, v2
	v_mov_b32_e32 v62, v2
	v_mov_b32_e32 v63, v2
	v_mov_b32_e32 v64, v2
	v_mov_b32_e32 v65, v2
	v_mov_b32_e32 v66, v2
	v_mov_b32_e32 v67, v2
	v_mov_b32_e32 v68, v2
	v_mov_b32_e32 v69, v2
	v_mov_b32_e32 v70, v2
	v_mov_b32_e32 v71, v2
	v_mov_b32_e32 v72, v2
	v_mov_b32_e32 v73, v2
	v_mov_b32_e32 v82, v2
	v_mov_b32_e32 v83, v2
	v_mov_b32_e32 v84, v2
	v_mov_b32_e32 v85, v2
	v_mov_b32_e32 v86, v2
	v_mov_b32_e32 v87, v2
	v_mov_b32_e32 v88, v2
	v_mov_b32_e32 v89, v2
	v_mov_b32_e32 v98, v2
	v_mov_b32_e32 v99, v2
	v_mov_b32_e32 v100, v2
	v_mov_b32_e32 v101, v2
	v_mov_b32_e32 v102, v2
	v_mov_b32_e32 v103, v2
	v_mov_b32_e32 v104, v2
	v_mov_b32_e32 v105, v2
	v_mov_b32_e32 v114, v2
	v_mov_b32_e32 v115, v2
	v_mov_b32_e32 v116, v2
	v_mov_b32_e32 v117, v2
	v_mov_b32_e32 v118, v2
	v_mov_b32_e32 v119, v2
	v_mov_b32_e32 v120, v2
	v_mov_b32_e32 v121, v2
	v_mov_b32_e32 v74, v2
	v_mov_b32_e32 v75, v2
	v_mov_b32_e32 v76, v2
	v_mov_b32_e32 v77, v2
	v_mov_b32_e32 v78, v2
	v_mov_b32_e32 v79, v2
	v_mov_b32_e32 v80, v2
	v_mov_b32_e32 v81, v2
	v_mov_b32_e32 v90, v2
	v_mov_b32_e32 v91, v2
	v_mov_b32_e32 v92, v2
	v_mov_b32_e32 v93, v2
	v_mov_b32_e32 v94, v2
	v_mov_b32_e32 v95, v2
	v_mov_b32_e32 v96, v2
	v_mov_b32_e32 v97, v2
	v_mov_b32_e32 v106, v2
	v_mov_b32_e32 v107, v2
	v_mov_b32_e32 v108, v2
	v_mov_b32_e32 v109, v2
	v_mov_b32_e32 v110, v2
	v_mov_b32_e32 v111, v2
	v_mov_b32_e32 v112, v2
	v_mov_b32_e32 v113, v2
	v_mov_b32_e32 v122, v2
	v_mov_b32_e32 v123, v2
	v_mov_b32_e32 v124, v2
	v_mov_b32_e32 v125, v2
	v_mov_b32_e32 v126, v2
	v_mov_b32_e32 v127, v2
	v_mov_b32_e32 v128, v2
	v_mov_b32_e32 v129, v2
.LBB0_162:
	ds_read_b128 v[130:133], v183
	ds_read_b128 v[134:137], v183 offset:1024
	ds_read_b128 v[138:141], v183 offset:2048
	ds_read_b128 v[142:145], v183 offset:3072
	ds_read_b128 v[172:175], v184
	ds_read_b128 v[176:179], v184 offset:1024
	ds_read_b128 v[192:195], v184 offset:2048
	ds_read_b128 v[196:199], v184 offset:3072
	s_add_u32 s50, s48, 0xfffc0080
	s_addc_u32 s51, s49, -1
	s_cmp_eq_u32 s93, 12
	s_cselect_b32 s65, s5, s51
	s_cselect_b32 s64, s34, s50
	s_cselect_b32 s51, s27, s92
	s_cselect_b32 s50, s35, s41
	v_lshl_add_u64 v[232:233], s[48:49], 0, v[164:165]
	s_add_i32 m0, s47, 0xc000
	ds_read_b128 v[200:203], v185
	ds_read_b128 v[204:207], v185 offset:1024
	ds_read_b128 v[208:211], v185 offset:2048
	ds_read_b128 v[212:215], v185 offset:3072
	ds_read_b128 v[216:219], v185 offset:4096
	ds_read_b128 v[220:223], v185 offset:5120
	ds_read_b128 v[224:227], v185 offset:6144
	ds_read_b128 v[228:231], v185 offset:7168
	global_load_lds_dwordx4 v[232:233], off
	v_lshl_add_u64 v[232:233], s[48:49], 0, v[166:167]
	s_add_i32 m0, s47, 0xe000
	s_nop 0
	global_load_lds_dwordx4 v[232:233], off
	s_waitcnt vmcnt(8)
	s_waitcnt lgkmcnt(0)
	s_barrier
; #define PG8_STAGE(bufoff, gbase, voff) do { _Pragma("unroll") for (int _i = 0; _i < 2; ++_i) \
;         __builtin_amdgcn_global_load_lds((const unsigned*)((const char*)(gbase) + (voff)[_i]), (PG8_LAS unsigned*)(lds + (bufoff) + ldsw + _i * 8192), 16, 0, 0); } while (0)
; #define PG8_LDA(dst, b, h) do { _Pragma("unroll") for (int m = 0; m < 4; ++m) _Pragma("unroll") for (int k = 0; k < 2; ++k) dst[m][k] = *(const PG8_LAS bf16x8*)(lds + PG8_SA(b, h) + aoff + m * 2048 + k * 1024); } while (0)
; #define PG8_LDB(dst, b, h) do { _Pragma("unroll") for (int n = 0; n < 2; ++n) _Pragma("unroll") for (int k = 0; k < 2; ++k) dst[n][k] = *(const PG8_LAS bf16x8*)(lds + PG8_SB(b, h) + boff + n * 2048 + k * 1024); } while (0)
; #define PG8_MMA(ai, bj, At, Bt) do { __builtin_amdgcn_s_setprio(1); _Pragma("unroll") for (int m = 0; m < 4; ++m) _Pragma("unroll") for (int n = 0; n < 2; ++n) _Pragma("unroll") for (int k = 0; k < 2; ++k) \
;         acc[ai][bj][m][n] = __builtin_amdgcn_mfma_f32_16x16x32_bf16(Bt[n][k], At[m][k], acc[ai][bj][m][n], 0, 0, 0); __builtin_amdgcn_s_setprio(0); } while (0)
; #define PG8_WAIT_V(n) asm volatile("s_waitcnt vmcnt(" #n ")" ::: "memory")
; #define PG8_WAIT_L(n) asm volatile("s_waitcnt lgkmcnt(" #n ")" ::: "memory")
; #define PG8_BAR __builtin_amdgcn_s_barrier()
; #define PG8_SCHED __builtin_amdgcn_sched_barrier(0)
; template <class Epi, class Sched, bool ALIGN_EPI = false, bool SP2 = false>
; __device__ __forceinline__ void gemm_phase(PG8_LAS unsigned char* lds, const Gemm g, const Sched& S, const Epi& E) {
;     ...
;             PG8_WAIT_V(8); PG8_WAIT_L(0); PG8_BAR; PG8_MMA(0, 0, At, B0); PG8_MMA(0, 1, At, B1); PG8_BAR; PG8_SCHED;
;             PG8_LDA(At, 0, 1); PG8_STAGE(PG8_SB(0, 0), b2, voffB); PG8_STAGE(PG8_SB(0, 1), b2 + hstep, voffB); PG8_STAGE(PG8_SA(0, 0), a2, voffA);
;             PG8_WAIT_V(8); PG8_WAIT_L(0); PG8_BAR; PG8_MMA(1, 0, At, B0); PG8_MMA(1, 1, At, B1); PG8_BAR; PG8_SCHED;
;             PG8_LDB(B0, 1, 0); PG8_LDB(B1, 1, 1); PG8_SCHED; PG8_LDA(At, 1, 0); PG8_STAGE(PG8_SA(0, 1), a2 + hstep, voffA);
	s_setprio 1
	s_waitcnt lgkmcnt(0)
	v_mfma_f32_16x16x32_bf16 v[126:129], v[130:133], v[200:203], v[126:129]
	v_mfma_f32_16x16x32_bf16 v[122:125], v[138:141], v[200:203], v[122:125]
	v_mfma_f32_16x16x32_bf16 v[110:113], v[130:133], v[208:211], v[110:113]
	v_mfma_f32_16x16x32_bf16 v[106:109], v[138:141], v[208:211], v[106:109]
	v_mfma_f32_16x16x32_bf16 v[94:97], v[130:133], v[216:219], v[94:97]
	v_mfma_f32_16x16x32_bf16 v[90:93], v[138:141], v[216:219], v[90:93]
	v_mfma_f32_16x16x32_bf16 v[78:81], v[130:133], v[224:227], v[78:81]
	v_mfma_f32_16x16x32_bf16 v[74:77], v[138:141], v[224:227], v[74:77]
	v_mfma_f32_16x16x32_bf16 v[126:129], v[134:137], v[204:207], v[126:129]
	v_mfma_f32_16x16x32_bf16 v[122:125], v[142:145], v[204:207], v[122:125]
	v_mfma_f32_16x16x32_bf16 v[110:113], v[134:137], v[212:215], v[110:113]
	v_mfma_f32_16x16x32_bf16 v[106:109], v[142:145], v[212:215], v[106:109]
	v_mfma_f32_16x16x32_bf16 v[94:97], v[134:137], v[220:223], v[94:97]
	v_mfma_f32_16x16x32_bf16 v[90:93], v[142:145], v[220:223], v[90:93]
	v_mfma_f32_16x16x32_bf16 v[78:81], v[134:137], v[228:231], v[78:81]
	v_mfma_f32_16x16x32_bf16 v[74:77], v[142:145], v[228:231], v[74:77]
	s_setprio 0
	s_setprio 1
	v_mfma_f32_16x16x32_bf16 v[118:121], v[172:175], v[200:203], v[118:121]
	v_mfma_f32_16x16x32_bf16 v[114:117], v[192:195], v[200:203], v[114:117]
	v_mfma_f32_16x16x32_bf16 v[102:105], v[172:175], v[208:211], v[102:105]
	v_mfma_f32_16x16x32_bf16 v[98:101], v[192:195], v[208:211], v[98:101]
	v_mfma_f32_16x16x32_bf16 v[86:89], v[172:175], v[216:219], v[86:89]
	v_mfma_f32_16x16x32_bf16 v[82:85], v[192:195], v[216:219], v[82:85]
	v_mfma_f32_16x16x32_bf16 v[70:73], v[172:175], v[224:227], v[70:73]
	v_mfma_f32_16x16x32_bf16 v[66:69], v[192:195], v[224:227], v[66:69]
	v_mfma_f32_16x16x32_bf16 v[118:121], v[176:179], v[204:207], v[118:121]
	v_mfma_f32_16x16x32_bf16 v[114:117], v[196:199], v[204:207], v[114:117]
	v_mfma_f32_16x16x32_bf16 v[102:105], v[176:179], v[212:215], v[102:105]
	v_mfma_f32_16x16x32_bf16 v[98:101], v[196:199], v[212:215], v[98:101]
	v_mfma_f32_16x16x32_bf16 v[86:89], v[176:179], v[220:223], v[86:89]
	v_mfma_f32_16x16x32_bf16 v[82:85], v[196:199], v[220:223], v[82:85]
	v_mfma_f32_16x16x32_bf16 v[70:73], v[176:179], v[228:231], v[70:73]
	v_mfma_f32_16x16x32_bf16 v[66:69], v[196:199], v[228:231], v[66:69]
	s_setprio 0
	s_barrier
	s_add_i32 s94, s85, s72
	v_lshl_add_u64 v[232:233], s[50:51], 0, v[148:149]
	s_mov_b32 m0, s94
	ds_read_b128 v[200:203], v185 offset:16384
	ds_read_b128 v[204:207], v185 offset:17408
	ds_read_b128 v[208:211], v185 offset:18432
	ds_read_b128 v[212:215], v185 offset:19456
	ds_read_b128 v[216:219], v185 offset:20480
	ds_read_b128 v[220:223], v185 offset:21504
	ds_read_b128 v[224:227], v185 offset:22528
	ds_read_b128 v[228:231], v185 offset:23552
	global_load_lds_dwordx4 v[232:233], off
	s_add_i32 m0, s94, 0x2000
	s_add_u32 s94, s50, 0x40000
	v_lshl_add_u64 v[234:235], s[50:51], 0, v[152:153]
	s_addc_u32 s95, s51, 0
	s_add_i32 s96, s86, s72
	global_load_lds_dwordx4 v[234:235], off
	v_lshl_add_u64 v[236:237], s[94:95], 0, v[148:149]
	s_mov_b32 m0, s96
	v_lshl_add_u64 v[238:239], s[64:65], 0, v[150:151]
	global_load_lds_dwordx4 v[236:237], off
	v_lshl_add_u64 v[236:237], s[94:95], 0, v[152:153]
	s_add_i32 m0, s96, 0x2000
	s_nop 0
	global_load_lds_dwordx4 v[236:237], off
	v_lshl_add_u64 v[236:237], s[64:65], 0, v[146:147]
	s_mov_b32 m0, s47
	s_nop 0
	global_load_lds_dwordx4 v[236:237], off
	s_mov_b32 m0, s73
	s_nop 0
	global_load_lds_dwordx4 v[238:239], off
	s_waitcnt vmcnt(8)
	s_waitcnt lgkmcnt(0)
	s_barrier
	s_setprio 1
	s_waitcnt lgkmcnt(0)
	v_mfma_f32_16x16x32_bf16 v[62:65], v[130:133], v[200:203], v[62:65]
	v_mfma_f32_16x16x32_bf16 v[58:61], v[138:141], v[200:203], v[58:61]
	v_mfma_f32_16x16x32_bf16 v[46:49], v[130:133], v[208:211], v[46:49]
	v_mfma_f32_16x16x32_bf16 v[42:45], v[138:141], v[208:211], v[42:45]
	v_mfma_f32_16x16x32_bf16 v[30:33], v[130:133], v[216:219], v[30:33]
	v_mfma_f32_16x16x32_bf16 v[26:29], v[138:141], v[216:219], v[26:29]
	v_mfma_f32_16x16x32_bf16 v[14:17], v[130:133], v[224:227], v[14:17]
	v_mfma_f32_16x16x32_bf16 v[10:13], v[138:141], v[224:227], v[10:13]
	v_mfma_f32_16x16x32_bf16 v[62:65], v[134:137], v[204:207], v[62:65]
	v_mfma_f32_16x16x32_bf16 v[58:61], v[142:145], v[204:207], v[58:61]
	v_mfma_f32_16x16x32_bf16 v[46:49], v[134:137], v[212:215], v[46:49]
	v_mfma_f32_16x16x32_bf16 v[42:45], v[142:145], v[212:215], v[42:45]
	v_mfma_f32_16x16x32_bf16 v[30:33], v[134:137], v[220:223], v[30:33]
	v_mfma_f32_16x16x32_bf16 v[26:29], v[142:145], v[220:223], v[26:29]
	v_mfma_f32_16x16x32_bf16 v[14:17], v[134:137], v[228:231], v[14:17]
	v_mfma_f32_16x16x32_bf16 v[10:13], v[142:145], v[228:231], v[10:13]
	s_setprio 0
	s_setprio 1
	v_mfma_f32_16x16x32_bf16 v[54:57], v[172:175], v[200:203], v[54:57]
	v_mfma_f32_16x16x32_bf16 v[50:53], v[192:195], v[200:203], v[50:53]
	v_mfma_f32_16x16x32_bf16 v[38:41], v[172:175], v[208:211], v[38:41]
	v_mfma_f32_16x16x32_bf16 v[34:37], v[192:195], v[208:211], v[34:37]
	v_mfma_f32_16x16x32_bf16 v[22:25], v[172:175], v[216:219], v[22:25]
	v_mfma_f32_16x16x32_bf16 v[18:21], v[192:195], v[216:219], v[18:21]
	v_mfma_f32_16x16x32_bf16 v[6:9], v[172:175], v[224:227], v[6:9]
	v_mfma_f32_16x16x32_bf16 v[2:5], v[192:195], v[224:227], v[2:5]
	v_mfma_f32_16x16x32_bf16 v[54:57], v[176:179], v[204:207], v[54:57]
	v_mfma_f32_16x16x32_bf16 v[50:53], v[196:199], v[204:207], v[50:53]
	v_mfma_f32_16x16x32_bf16 v[38:41], v[176:179], v[212:215], v[38:41]
	v_mfma_f32_16x16x32_bf16 v[34:37], v[196:199], v[212:215], v[34:37]
	v_mfma_f32_16x16x32_bf16 v[22:25], v[176:179], v[220:223], v[22:25]
	v_mfma_f32_16x16x32_bf16 v[18:21], v[196:199], v[220:223], v[18:21]
	v_mfma_f32_16x16x32_bf16 v[6:9], v[176:179], v[228:231], v[6:9]
	v_mfma_f32_16x16x32_bf16 v[2:5], v[196:199], v[228:231], v[2:5]
	s_setprio 0
	s_barrier
; #define PG8_STAGE(bufoff, gbase, voff) do { _Pragma("unroll") for (int _i = 0; _i < 2; ++_i) \
;         __builtin_amdgcn_global_load_lds((const unsigned*)((const char*)(gbase) + (voff)[_i]), (PG8_LAS unsigned*)(lds + (bufoff) + ldsw + _i * 8192), 16, 0, 0); } while (0)
; #define PG8_LDA(dst, b, h) do { _Pragma("unroll") for (int m = 0; m < 4; ++m) _Pragma("unroll") for (int k = 0; k < 2; ++k) dst[m][k] = *(const PG8_LAS bf16x8*)(lds + PG8_SA(b, h) + aoff + m * 2048 + k * 1024); } while (0)
; #define PG8_LDB(dst, b, h) do { _Pragma("unroll") for (int n = 0; n < 2; ++n) _Pragma("unroll") for (int k = 0; k < 2; ++k) dst[n][k] = *(const PG8_LAS bf16x8*)(lds + PG8_SB(b, h) + boff + n * 2048 + k * 1024); } while (0)
; #define PG8_MMA(ai, bj, At, Bt) do { __builtin_amdgcn_s_setprio(1); _Pragma("unroll") for (int m = 0; m < 4; ++m) _Pragma("unroll") for (int n = 0; n < 2; ++n) _Pragma("unroll") for (int k = 0; k < 2; ++k) \
;         acc[ai][bj][m][n] = __builtin_amdgcn_mfma_f32_16x16x32_bf16(Bt[n][k], At[m][k], acc[ai][bj][m][n], 0, 0, 0); __builtin_amdgcn_s_setprio(0); } while (0)
; #define PG8_WAIT_V(n) asm volatile("s_waitcnt vmcnt(" #n ")" ::: "memory")
; #define PG8_WAIT_L(n) asm volatile("s_waitcnt lgkmcnt(" #n ")" ::: "memory")
; #define PG8_BAR __builtin_amdgcn_s_barrier()
; #define PG8_SCHED __builtin_amdgcn_sched_barrier(0)
; template <class Epi, class Sched, bool ALIGN_EPI = false, bool SP2 = false>
; __device__ __forceinline__ void gemm_phase(PG8_LAS unsigned char* lds, const Gemm g, const Sched& S, const Epi& E) {
;     ...
;             PG8_LDB(B0, 1, 0); PG8_LDB(B1, 1, 1); PG8_SCHED; PG8_LDA(At, 1, 0); PG8_STAGE(PG8_SA(0, 1), a2 + hstep, voffA);
;             PG8_WAIT_V(8); PG8_WAIT_L(0); PG8_BAR; PG8_MMA(0, 0, At, B0); PG8_MMA(0, 1, At, B1); PG8_BAR; PG8_SCHED;
	s_add_i32 s94, 0, 0x18000
	s_add_i32 s95, 0, 0x1c000
	v_add_u32_e32 v142, s94, v181
	v_add_u32_e32 v154, s95, v181
	ds_read_b128 v[130:133], v142
	ds_read_b128 v[134:137], v142 offset:1024
	ds_read_b128 v[138:141], v142 offset:2048
	ds_read_b128 v[142:145], v142 offset:3072
	ds_read_b128 v[172:175], v154
	ds_read_b128 v[176:179], v154 offset:1024
	ds_read_b128 v[192:195], v154 offset:2048
	ds_read_b128 v[196:199], v154 offset:3072
	s_add_u32 s64, s64, 0x40000
	s_addc_u32 s65, s65, 0
	s_mov_b32 m0, s74
	v_lshl_add_u64 v[240:241], s[64:65], 0, v[146:147]
	ds_read_b128 v[200:203], v185 offset:32768
	ds_read_b128 v[204:207], v185 offset:33792
	ds_read_b128 v[208:211], v185 offset:34816
	ds_read_b128 v[212:215], v185 offset:35840
	ds_read_b128 v[216:219], v185 offset:36864
	ds_read_b128 v[220:223], v185 offset:37888
	ds_read_b128 v[224:227], v185 offset:38912
	ds_read_b128 v[228:231], v185 offset:39936
	global_load_lds_dwordx4 v[240:241], off
	v_lshl_add_u64 v[240:241], s[64:65], 0, v[150:151]
	s_mov_b32 m0, s75
	s_nop 0
	global_load_lds_dwordx4 v[240:241], off
	s_waitcnt vmcnt(8)
	s_waitcnt lgkmcnt(0)
	s_barrier
	s_setprio 1
	s_waitcnt lgkmcnt(0)
	v_mfma_f32_16x16x32_bf16 v[126:129], v[130:133], v[200:203], v[126:129]
	v_mfma_f32_16x16x32_bf16 v[122:125], v[138:141], v[200:203], v[122:125]
	v_mfma_f32_16x16x32_bf16 v[110:113], v[130:133], v[208:211], v[110:113]
	v_mfma_f32_16x16x32_bf16 v[106:109], v[138:141], v[208:211], v[106:109]
	v_mfma_f32_16x16x32_bf16 v[94:97], v[130:133], v[216:219], v[94:97]
	v_mfma_f32_16x16x32_bf16 v[90:93], v[138:141], v[216:219], v[90:93]
	v_mfma_f32_16x16x32_bf16 v[78:81], v[130:133], v[224:227], v[78:81]
	v_mfma_f32_16x16x32_bf16 v[74:77], v[138:141], v[224:227], v[74:77]
	v_mfma_f32_16x16x32_bf16 v[126:129], v[134:137], v[204:207], v[126:129]
	v_mfma_f32_16x16x32_bf16 v[122:125], v[142:145], v[204:207], v[122:125]
	v_mfma_f32_16x16x32_bf16 v[110:113], v[134:137], v[212:215], v[110:113]
	v_mfma_f32_16x16x32_bf16 v[106:109], v[142:145], v[212:215], v[106:109]
	v_mfma_f32_16x16x32_bf16 v[94:97], v[134:137], v[220:223], v[94:97]
	v_mfma_f32_16x16x32_bf16 v[90:93], v[142:145], v[220:223], v[90:93]
	v_mfma_f32_16x16x32_bf16 v[78:81], v[134:137], v[228:231], v[78:81]
	v_mfma_f32_16x16x32_bf16 v[74:77], v[142:145], v[228:231], v[74:77]
	s_setprio 0
	s_setprio 1
	v_mfma_f32_16x16x32_bf16 v[118:121], v[172:175], v[200:203], v[118:121]
	v_mfma_f32_16x16x32_bf16 v[114:117], v[192:195], v[200:203], v[114:117]
	v_mfma_f32_16x16x32_bf16 v[102:105], v[172:175], v[208:211], v[102:105]
	v_mfma_f32_16x16x32_bf16 v[98:101], v[192:195], v[208:211], v[98:101]
	v_mfma_f32_16x16x32_bf16 v[86:89], v[172:175], v[216:219], v[86:89]
	v_mfma_f32_16x16x32_bf16 v[82:85], v[192:195], v[216:219], v[82:85]
	v_mfma_f32_16x16x32_bf16 v[70:73], v[172:175], v[224:227], v[70:73]
	v_mfma_f32_16x16x32_bf16 v[66:69], v[192:195], v[224:227], v[66:69]
	v_mfma_f32_16x16x32_bf16 v[118:121], v[176:179], v[204:207], v[118:121]
	v_mfma_f32_16x16x32_bf16 v[114:117], v[196:199], v[204:207], v[114:117]
	v_mfma_f32_16x16x32_bf16 v[102:105], v[176:179], v[212:215], v[102:105]
	v_mfma_f32_16x16x32_bf16 v[98:101], v[196:199], v[212:215], v[98:101]
	v_mfma_f32_16x16x32_bf16 v[86:89], v[176:179], v[220:223], v[86:89]
	v_mfma_f32_16x16x32_bf16 v[82:85], v[196:199], v[220:223], v[82:85]
	v_mfma_f32_16x16x32_bf16 v[70:73], v[176:179], v[228:231], v[70:73]
	v_mfma_f32_16x16x32_bf16 v[66:69], v[196:199], v[228:231], v[66:69]
	s_setprio 0
	s_barrier
; #define PG8_STAGE(bufoff, gbase, voff) do { _Pragma("unroll") for (int _i = 0; _i < 2; ++_i) \
;         __builtin_amdgcn_global_load_lds((const unsigned*)((const char*)(gbase) + (voff)[_i]), (PG8_LAS unsigned*)(lds + (bufoff) + ldsw + _i * 8192), 16, 0, 0); } while (0)
; #define PG8_LDA(dst, b, h) do { _Pragma("unroll") for (int m = 0; m < 4; ++m) _Pragma("unroll") for (int k = 0; k < 2; ++k) dst[m][k] = *(const PG8_LAS bf16x8*)(lds + PG8_SA(b, h) + aoff + m * 2048 + k * 1024); } while (0)
; #define PG8_LDB(dst, b, h) do { _Pragma("unroll") for (int n = 0; n < 2; ++n) _Pragma("unroll") for (int k = 0; k < 2; ++k) dst[n][k] = *(const PG8_LAS bf16x8*)(lds + PG8_SB(b, h) + boff + n * 2048 + k * 1024); } while (0)
; #define PG8_MMA(ai, bj, At, Bt) do { __builtin_amdgcn_s_setprio(1); _Pragma("unroll") for (int m = 0; m < 4; ++m) _Pragma("unroll") for (int n = 0; n < 2; ++n) _Pragma("unroll") for (int k = 0; k < 2; ++k) \
;         acc[ai][bj][m][n] = __builtin_amdgcn_mfma_f32_16x16x32_bf16(Bt[n][k], At[m][k], acc[ai][bj][m][n], 0, 0, 0); __builtin_amdgcn_s_setprio(0); } while (0)
; #define PG8_WAIT_V(n) asm volatile("s_waitcnt vmcnt(" #n ")" ::: "memory")
; #define PG8_WAIT_L(n) asm volatile("s_waitcnt lgkmcnt(" #n ")" ::: "memory")
; #define PG8_BAR __builtin_amdgcn_s_barrier()
; #define PG8_SCHED __builtin_amdgcn_sched_barrier(0)
; template <class Epi, class Sched, bool ALIGN_EPI = false, bool SP2 = false>
; __device__ __forceinline__ void gemm_phase(PG8_LAS unsigned char* lds, const Gemm g, const Sched& S, const Epi& E) {
;     ...
;             PG8_LDB(B0, 0, 0); PG8_LDB(B1, 0, 1); PG8_SCHED; PG8_LDA(At, 0, 0); PG8_STAGE(PG8_SA(1, 1), a1 + hstep, voffA);
;     ...
;             PG8_LDA(At, 1, 1); PG8_STAGE(PG8_SB(1, 0), b3, voffB); PG8_STAGE(PG8_SB(1, 1), b3 + hstep, voffB); PG8_STAGE(PG8_SA(1, 0), a3, voffA);
;             PG8_WAIT_V(8); PG8_WAIT_L(0); PG8_BAR; PG8_MMA(1, 0, At, B0); PG8_MMA(1, 1, At, B1); PG8_BAR; PG8_SCHED;
	s_add_i32 s64, s94, s72
	v_lshl_add_u64 v[232:233], v[232:233], 0, s[12:13]
	s_mov_b32 m0, s64
	ds_read_b128 v[200:203], v185 offset:49152
	ds_read_b128 v[204:207], v185 offset:50176
	ds_read_b128 v[208:211], v185 offset:51200
	ds_read_b128 v[212:215], v185 offset:52224
	ds_read_b128 v[216:219], v185 offset:53248
	ds_read_b128 v[220:223], v185 offset:54272
	ds_read_b128 v[224:227], v185 offset:55296
	ds_read_b128 v[228:231], v185 offset:56320
	global_load_lds_dwordx4 v[232:233], off
	s_add_i32 m0, s64, 0x2000
	s_add_u32 s50, s50, 0x40080
	v_lshl_add_u64 v[232:233], v[234:235], 0, s[12:13]
	s_addc_u32 s51, s51, 0
	s_add_i32 s64, s95, s72
	global_load_lds_dwordx4 v[232:233], off
	v_lshl_add_u64 v[232:233], s[50:51], 0, v[148:149]
	s_mov_b32 m0, s64
	s_nop 0
	global_load_lds_dwordx4 v[232:233], off
	v_lshl_add_u64 v[232:233], s[50:51], 0, v[152:153]
	s_add_i32 m0, s64, 0x2000
	s_nop 0
	global_load_lds_dwordx4 v[232:233], off
	v_lshl_add_u64 v[232:233], v[236:237], 0, s[12:13]
	s_mov_b32 m0, s82
	s_nop 0
	global_load_lds_dwordx4 v[232:233], off
	v_lshl_add_u64 v[232:233], v[238:239], 0, s[12:13]
	s_mov_b32 m0, s83
	s_nop 0
	global_load_lds_dwordx4 v[232:233], off
	s_waitcnt vmcnt(8)
	s_waitcnt lgkmcnt(0)
	s_barrier
	s_setprio 1
	s_waitcnt lgkmcnt(0)
	v_mfma_f32_16x16x32_bf16 v[62:65], v[130:133], v[200:203], v[62:65]
	v_mfma_f32_16x16x32_bf16 v[58:61], v[138:141], v[200:203], v[58:61]
	v_mfma_f32_16x16x32_bf16 v[46:49], v[130:133], v[208:211], v[46:49]
	v_mfma_f32_16x16x32_bf16 v[42:45], v[138:141], v[208:211], v[42:45]
	v_mfma_f32_16x16x32_bf16 v[30:33], v[130:133], v[216:219], v[30:33]
	v_mfma_f32_16x16x32_bf16 v[26:29], v[138:141], v[216:219], v[26:29]
	v_mfma_f32_16x16x32_bf16 v[14:17], v[130:133], v[224:227], v[14:17]
	v_mfma_f32_16x16x32_bf16 v[10:13], v[138:141], v[224:227], v[10:13]
	v_mfma_f32_16x16x32_bf16 v[62:65], v[134:137], v[204:207], v[62:65]
	v_mfma_f32_16x16x32_bf16 v[58:61], v[142:145], v[204:207], v[58:61]
	v_mfma_f32_16x16x32_bf16 v[46:49], v[134:137], v[212:215], v[46:49]
	v_mfma_f32_16x16x32_bf16 v[42:45], v[142:145], v[212:215], v[42:45]
	v_mfma_f32_16x16x32_bf16 v[30:33], v[134:137], v[220:223], v[30:33]
	v_mfma_f32_16x16x32_bf16 v[26:29], v[142:145], v[220:223], v[26:29]
	v_mfma_f32_16x16x32_bf16 v[14:17], v[134:137], v[228:231], v[14:17]
	v_mfma_f32_16x16x32_bf16 v[10:13], v[142:145], v[228:231], v[10:13]
	s_setprio 0
	s_setprio 1
	v_mfma_f32_16x16x32_bf16 v[54:57], v[172:175], v[200:203], v[54:57]
	v_mfma_f32_16x16x32_bf16 v[50:53], v[192:195], v[200:203], v[50:53]
	v_mfma_f32_16x16x32_bf16 v[38:41], v[172:175], v[208:211], v[38:41]
	v_mfma_f32_16x16x32_bf16 v[34:37], v[192:195], v[208:211], v[34:37]
	v_mfma_f32_16x16x32_bf16 v[22:25], v[172:175], v[216:219], v[22:25]
	v_mfma_f32_16x16x32_bf16 v[18:21], v[192:195], v[216:219], v[18:21]
	v_mfma_f32_16x16x32_bf16 v[6:9], v[172:175], v[224:227], v[6:9]
	v_mfma_f32_16x16x32_bf16 v[2:5], v[192:195], v[224:227], v[2:5]
	v_mfma_f32_16x16x32_bf16 v[54:57], v[176:179], v[204:207], v[54:57]
	v_mfma_f32_16x16x32_bf16 v[50:53], v[196:199], v[204:207], v[50:53]
	v_mfma_f32_16x16x32_bf16 v[38:41], v[176:179], v[212:215], v[38:41]
	v_mfma_f32_16x16x32_bf16 v[34:37], v[196:199], v[212:215], v[34:37]
	v_mfma_f32_16x16x32_bf16 v[22:25], v[176:179], v[220:223], v[22:25]
	v_mfma_f32_16x16x32_bf16 v[18:21], v[196:199], v[220:223], v[18:21]
	v_mfma_f32_16x16x32_bf16 v[6:9], v[176:179], v[228:231], v[6:9]
	v_mfma_f32_16x16x32_bf16 v[2:5], v[196:199], v[228:231], v[2:5]
	s_setprio 0
	s_barrier
	s_add_i32 s93, s93, 2
	s_add_u32 s48, s48, 0x100
	s_addc_u32 s49, s49, 0
	s_add_u32 s41, s41, 0x100
	s_addc_u32 s92, s92, 0
	s_cmp_gt_u32 s93, 13
	s_cbranch_scc0 .LBB0_162
	s_add_u32 s94, s34, 0x40080
	s_addc_u32 s95, s5, 0
	v_lshl_add_u64 v[232:233], s[94:95], 0, v[164:165]
	s_add_i32 m0, s47, 0xc000
	v_lshl_add_u64 v[234:235], s[94:95], 0, v[166:167]
	global_load_lds_dwordx4 v[232:233], off
	s_add_i32 m0, s47, 0xe000
	s_nop 0
	global_load_lds_dwordx4 v[234:235], off
	s_and_b64 vcc, exec, s[14:15]
	s_cbranch_vccz .LBB0_165
	s_barrier

; #define PG8_STAGE(bufoff, gbase, voff) do { _Pragma("unroll") for (int _i = 0; _i < 2; ++_i) \
;         __builtin_amdgcn_global_load_lds((const unsigned*)((const char*)(gbase) + (voff)[_i]), (PG8_LAS unsigned*)(lds + (bufoff) + ldsw + _i * 8192), 16, 0, 0); } while (0)
; #define PG8_LDA(dst, b, h) do { _Pragma("unroll") for (int m = 0; m < 4; ++m) _Pragma("unroll") for (int k = 0; k < 2; ++k) dst[m][k] = *(const PG8_LAS bf16x8*)(lds + PG8_SA(b, h) + aoff + m * 2048 + k * 1024); } while (0)
; #define PG8_LDB(dst, b, h) do { _Pragma("unroll") for (int n = 0; n < 2; ++n) _Pragma("unroll") for (int k = 0; k < 2; ++k) dst[n][k] = *(const PG8_LAS bf16x8*)(lds + PG8_SB(b, h) + boff + n * 2048 + k * 1024); } while (0)
; #define PG8_MMA(ai, bj, At, Bt) do { __builtin_amdgcn_s_setprio(1); _Pragma("unroll") for (int m = 0; m < 4; ++m) _Pragma("unroll") for (int n = 0; n < 2; ++n) _Pragma("unroll") for (int k = 0; k < 2; ++k) \
;         acc[ai][bj][m][n] = __builtin_amdgcn_mfma_f32_16x16x32_bf16(Bt[n][k], At[m][k], acc[ai][bj][m][n], 0, 0, 0); __builtin_amdgcn_s_setprio(0); } while (0)
; #define PG8_WAIT_V(n) asm volatile("s_waitcnt vmcnt(" #n ")" ::: "memory")
; #define PG8_WAIT_L(n) asm volatile("s_waitcnt lgkmcnt(" #n ")" ::: "memory")
; #define PG8_BAR __builtin_amdgcn_s_barrier()
; #define PG8_SCHED __builtin_amdgcn_sched_barrier(0)
; template <class Epi, class Sched, bool ALIGN_EPI = false, bool SP2 = false>
; __device__ __forceinline__ void gemm_phase(PG8_LAS unsigned char* lds, const Gemm g, const Sched& S, const Epi& E) {
;     ...
;             PG8_LDB(B0, 0, 0); PG8_LDB(B1, 0, 1); PG8_SCHED; PG8_LDA(At, 0, 0); PG8_STAGE(PG8_SA(1, 1), a1 + hstep, voffA);
;             PG8_WAIT_V(8); PG8_WAIT_L(0); PG8_BAR; PG8_MMA(0, 0, At, B0); PG8_MMA(0, 1, At, B1); PG8_BAR; PG8_SCHED;
;             PG8_LDA(At, 0, 1); PG8_STAGE(PG8_SB(0, 0), b2, voffB); PG8_STAGE(PG8_SB(0, 1), b2 + hstep, voffB); PG8_STAGE(PG8_SA(0, 0), a2, voffA);
;             PG8_WAIT_V(8); PG8_WAIT_L(0); PG8_BAR; PG8_MMA(1, 0, At, B0); PG8_MMA(1, 1, At, B1); PG8_BAR; PG8_SCHED;
.Lp1_peel:
	ds_read_b128 v[130:133], v183
	ds_read_b128 v[134:137], v183 offset:1024
	ds_read_b128 v[138:141], v183 offset:2048
	ds_read_b128 v[142:145], v183 offset:3072
	ds_read_b128 v[172:175], v184
	ds_read_b128 v[176:179], v184 offset:1024
	ds_read_b128 v[192:195], v184 offset:2048
	ds_read_b128 v[196:199], v184 offset:3072
	s_add_u32 s50, s48, 0xfffc0080
	s_addc_u32 s51, s49, -1
	s_cmp_eq_u32 s93, 12
	s_cselect_b32 s65, s5, s51
	s_cselect_b32 s64, s34, s50
	s_cselect_b32 s51, s27, s92
	s_cselect_b32 s50, s35, s41
	ds_read_b128 v[200:203], v185
	ds_read_b128 v[204:207], v185 offset:1024
	ds_read_b128 v[208:211], v185 offset:2048
	ds_read_b128 v[212:215], v185 offset:3072
	ds_read_b128 v[216:219], v185 offset:4096
	ds_read_b128 v[220:223], v185 offset:5120
	ds_read_b128 v[224:227], v185 offset:6144
	ds_read_b128 v[228:231], v185 offset:7168
	s_waitcnt vmcnt(24)
	s_waitcnt lgkmcnt(0)
	s_barrier
	s_setprio 1
	s_waitcnt lgkmcnt(0)
	v_mfma_f32_16x16x32_bf16 v[126:129], v[130:133], v[200:203], 0
	v_mfma_f32_16x16x32_bf16 v[122:125], v[138:141], v[200:203], 0
	v_mfma_f32_16x16x32_bf16 v[110:113], v[130:133], v[208:211], 0
	v_mfma_f32_16x16x32_bf16 v[106:109], v[138:141], v[208:211], 0
	v_mfma_f32_16x16x32_bf16 v[94:97], v[130:133], v[216:219], 0
	v_mfma_f32_16x16x32_bf16 v[90:93], v[138:141], v[216:219], 0
	v_mfma_f32_16x16x32_bf16 v[78:81], v[130:133], v[224:227], 0
	v_mfma_f32_16x16x32_bf16 v[74:77], v[138:141], v[224:227], 0
	v_mfma_f32_16x16x32_bf16 v[126:129], v[134:137], v[204:207], v[126:129]
	v_mfma_f32_16x16x32_bf16 v[122:125], v[142:145], v[204:207], v[122:125]
	v_mfma_f32_16x16x32_bf16 v[110:113], v[134:137], v[212:215], v[110:113]
	v_mfma_f32_16x16x32_bf16 v[106:109], v[142:145], v[212:215], v[106:109]
	v_mfma_f32_16x16x32_bf16 v[94:97], v[134:137], v[220:223], v[94:97]
	v_mfma_f32_16x16x32_bf16 v[90:93], v[142:145], v[220:223], v[90:93]
	v_mfma_f32_16x16x32_bf16 v[78:81], v[134:137], v[228:231], v[78:81]
	v_mfma_f32_16x16x32_bf16 v[74:77], v[142:145], v[228:231], v[74:77]
	s_setprio 0
	s_setprio 1
	v_mfma_f32_16x16x32_bf16 v[118:121], v[172:175], v[200:203], 0
	v_mfma_f32_16x16x32_bf16 v[114:117], v[192:195], v[200:203], 0
	v_mfma_f32_16x16x32_bf16 v[102:105], v[172:175], v[208:211], 0
	v_mfma_f32_16x16x32_bf16 v[98:101], v[192:195], v[208:211], 0
	v_mfma_f32_16x16x32_bf16 v[86:89], v[172:175], v[216:219], 0
	v_mfma_f32_16x16x32_bf16 v[82:85], v[192:195], v[216:219], 0
	v_mfma_f32_16x16x32_bf16 v[70:73], v[172:175], v[224:227], 0
	v_mfma_f32_16x16x32_bf16 v[66:69], v[192:195], v[224:227], 0
	v_mfma_f32_16x16x32_bf16 v[118:121], v[176:179], v[204:207], v[118:121]
	v_mfma_f32_16x16x32_bf16 v[114:117], v[196:199], v[204:207], v[114:117]
	v_mfma_f32_16x16x32_bf16 v[102:105], v[176:179], v[212:215], v[102:105]
	v_mfma_f32_16x16x32_bf16 v[98:101], v[196:199], v[212:215], v[98:101]
	v_mfma_f32_16x16x32_bf16 v[86:89], v[176:179], v[220:223], v[86:89]
	v_mfma_f32_16x16x32_bf16 v[82:85], v[196:199], v[220:223], v[82:85]
	v_mfma_f32_16x16x32_bf16 v[70:73], v[176:179], v[228:231], v[70:73]
	v_mfma_f32_16x16x32_bf16 v[66:69], v[196:199], v[228:231], v[66:69]
	s_setprio 0
	s_barrier
	s_add_i32 s94, s85, s72
	v_lshl_add_u64 v[232:233], s[50:51], 0, v[148:149]
	s_mov_b32 m0, s94
	ds_read_b128 v[200:203], v185 offset:16384
	ds_read_b128 v[204:207], v185 offset:17408
	ds_read_b128 v[208:211], v185 offset:18432
	ds_read_b128 v[212:215], v185 offset:19456
	ds_read_b128 v[216:219], v185 offset:20480
	ds_read_b128 v[220:223], v185 offset:21504
	ds_read_b128 v[224:227], v185 offset:22528
	ds_read_b128 v[228:231], v185 offset:23552
	global_load_lds_dwordx4 v[232:233], off
	s_add_i32 m0, s94, 0x2000
	s_add_u32 s94, s50, 0x40000
	v_lshl_add_u64 v[234:235], s[50:51], 0, v[152:153]
	s_addc_u32 s95, s51, 0
	s_add_i32 s96, s86, s72
	global_load_lds_dwordx4 v[234:235], off
	v_lshl_add_u64 v[236:237], s[94:95], 0, v[148:149]
	s_mov_b32 m0, s96
	v_lshl_add_u64 v[238:239], s[64:65], 0, v[150:151]
	global_load_lds_dwordx4 v[236:237], off
	v_lshl_add_u64 v[236:237], s[94:95], 0, v[152:153]
	s_add_i32 m0, s96, 0x2000
	s_nop 0
	global_load_lds_dwordx4 v[236:237], off
	v_lshl_add_u64 v[236:237], s[64:65], 0, v[146:147]
	s_mov_b32 m0, s47
	s_nop 0
	global_load_lds_dwordx4 v[236:237], off
	s_mov_b32 m0, s73
	s_nop 0
	global_load_lds_dwordx4 v[238:239], off
	s_waitcnt vmcnt(24)
	s_waitcnt lgkmcnt(0)
	s_barrier
	s_setprio 1
	s_waitcnt lgkmcnt(0)
	v_mfma_f32_16x16x32_bf16 v[62:65], v[130:133], v[200:203], 0
	v_mfma_f32_16x16x32_bf16 v[58:61], v[138:141], v[200:203], 0
	v_mfma_f32_16x16x32_bf16 v[46:49], v[130:133], v[208:211], 0
	v_mfma_f32_16x16x32_bf16 v[42:45], v[138:141], v[208:211], 0
	v_mfma_f32_16x16x32_bf16 v[30:33], v[130:133], v[216:219], 0
	v_mfma_f32_16x16x32_bf16 v[26:29], v[138:141], v[216:219], 0
	v_mfma_f32_16x16x32_bf16 v[14:17], v[130:133], v[224:227], 0
	v_mfma_f32_16x16x32_bf16 v[10:13], v[138:141], v[224:227], 0
	v_mfma_f32_16x16x32_bf16 v[62:65], v[134:137], v[204:207], v[62:65]
	v_mfma_f32_16x16x32_bf16 v[58:61], v[142:145], v[204:207], v[58:61]
	v_mfma_f32_16x16x32_bf16 v[46:49], v[134:137], v[212:215], v[46:49]
	v_mfma_f32_16x16x32_bf16 v[42:45], v[142:145], v[212:215], v[42:45]
	v_mfma_f32_16x16x32_bf16 v[30:33], v[134:137], v[220:223], v[30:33]
	v_mfma_f32_16x16x32_bf16 v[26:29], v[142:145], v[220:223], v[26:29]
	v_mfma_f32_16x16x32_bf16 v[14:17], v[134:137], v[228:231], v[14:17]
	v_mfma_f32_16x16x32_bf16 v[10:13], v[142:145], v[228:231], v[10:13]
	s_setprio 0
	s_setprio 1
	v_mfma_f32_16x16x32_bf16 v[54:57], v[172:175], v[200:203], 0
	v_mfma_f32_16x16x32_bf16 v[50:53], v[192:195], v[200:203], 0
	v_mfma_f32_16x16x32_bf16 v[38:41], v[172:175], v[208:211], 0
	v_mfma_f32_16x16x32_bf16 v[34:37], v[192:195], v[208:211], 0
	v_mfma_f32_16x16x32_bf16 v[22:25], v[172:175], v[216:219], 0
	v_mfma_f32_16x16x32_bf16 v[18:21], v[192:195], v[216:219], 0
	v_mfma_f32_16x16x32_bf16 v[6:9], v[172:175], v[224:227], 0
	v_mfma_f32_16x16x32_bf16 v[2:5], v[192:195], v[224:227], 0
	v_mfma_f32_16x16x32_bf16 v[54:57], v[176:179], v[204:207], v[54:57]
	v_mfma_f32_16x16x32_bf16 v[50:53], v[196:199], v[204:207], v[50:53]
	v_mfma_f32_16x16x32_bf16 v[38:41], v[176:179], v[212:215], v[38:41]
	v_mfma_f32_16x16x32_bf16 v[34:37], v[196:199], v[212:215], v[34:37]
	v_mfma_f32_16x16x32_bf16 v[22:25], v[176:179], v[220:223], v[22:25]
	v_mfma_f32_16x16x32_bf16 v[18:21], v[196:199], v[220:223], v[18:21]
	v_mfma_f32_16x16x32_bf16 v[6:9], v[176:179], v[228:231], v[6:9]
	v_mfma_f32_16x16x32_bf16 v[2:5], v[196:199], v[228:231], v[2:5]
	s_setprio 0
	s_barrier
; #define PG8_STAGE(bufoff, gbase, voff) do { _Pragma("unroll") for (int _i = 0; _i < 2; ++_i) \
;         __builtin_amdgcn_global_load_lds((const unsigned*)((const char*)(gbase) + (voff)[_i]), (PG8_LAS unsigned*)(lds + (bufoff) + ldsw + _i * 8192), 16, 0, 0); } while (0)
; #define PG8_LDA(dst, b, h) do { _Pragma("unroll") for (int m = 0; m < 4; ++m) _Pragma("unroll") for (int k = 0; k < 2; ++k) dst[m][k] = *(const PG8_LAS bf16x8*)(lds + PG8_SA(b, h) + aoff + m * 2048 + k * 1024); } while (0)
; #define PG8_LDB(dst, b, h) do { _Pragma("unroll") for (int n = 0; n < 2; ++n) _Pragma("unroll") for (int k = 0; k < 2; ++k) dst[n][k] = *(const PG8_LAS bf16x8*)(lds + PG8_SB(b, h) + boff + n * 2048 + k * 1024); } while (0)
; #define PG8_MMA(ai, bj, At, Bt) do { __builtin_amdgcn_s_setprio(1); _Pragma("unroll") for (int m = 0; m < 4; ++m) _Pragma("unroll") for (int n = 0; n < 2; ++n) _Pragma("unroll") for (int k = 0; k < 2; ++k) \
;         acc[ai][bj][m][n] = __builtin_amdgcn_mfma_f32_16x16x32_bf16(Bt[n][k], At[m][k], acc[ai][bj][m][n], 0, 0, 0); __builtin_amdgcn_s_setprio(0); } while (0)
; #define PG8_WAIT_V(n) asm volatile("s_waitcnt vmcnt(" #n ")" ::: "memory")
; #define PG8_WAIT_L(n) asm volatile("s_waitcnt lgkmcnt(" #n ")" ::: "memory")
; #define PG8_BAR __builtin_amdgcn_s_barrier()
; #define PG8_SCHED __builtin_amdgcn_sched_barrier(0)
; template <class Epi, class Sched, bool ALIGN_EPI = false, bool SP2 = false>
; __device__ __forceinline__ void gemm_phase(PG8_LAS unsigned char* lds, const Gemm g, const Sched& S, const Epi& E) {
;     ...
;             PG8_LDB(B0, 1, 0); PG8_LDB(B1, 1, 1); PG8_SCHED; PG8_LDA(At, 1, 0); PG8_STAGE(PG8_SA(0, 1), a2 + hstep, voffA);
;             PG8_WAIT_V(8); PG8_WAIT_L(0); PG8_BAR; PG8_MMA(0, 0, At, B0); PG8_MMA(0, 1, At, B1); PG8_BAR; PG8_SCHED;
	s_add_i32 s94, 0, 0x18000
	s_add_i32 s95, 0, 0x1c000
	v_add_u32_e32 v142, s94, v181
	v_add_u32_e32 v154, s95, v181
	ds_read_b128 v[130:133], v142
	ds_read_b128 v[134:137], v142 offset:1024
	ds_read_b128 v[138:141], v142 offset:2048
	ds_read_b128 v[142:145], v142 offset:3072
	ds_read_b128 v[172:175], v154
	ds_read_b128 v[176:179], v154 offset:1024
	ds_read_b128 v[192:195], v154 offset:2048
	ds_read_b128 v[196:199], v154 offset:3072
	s_add_u32 s64, s64, 0x40000
	s_addc_u32 s65, s65, 0
	s_mov_b32 m0, s74
	v_lshl_add_u64 v[240:241], s[64:65], 0, v[146:147]
	ds_read_b128 v[200:203], v185 offset:32768
	ds_read_b128 v[204:207], v185 offset:33792
	ds_read_b128 v[208:211], v185 offset:34816
	ds_read_b128 v[212:215], v185 offset:35840
	ds_read_b128 v[216:219], v185 offset:36864
	ds_read_b128 v[220:223], v185 offset:37888
	ds_read_b128 v[224:227], v185 offset:38912
	ds_read_b128 v[228:231], v185 offset:39936
	global_load_lds_dwordx4 v[240:241], off
	v_lshl_add_u64 v[240:241], s[64:65], 0, v[150:151]
	s_mov_b32 m0, s75
	s_nop 0
	global_load_lds_dwordx4 v[240:241], off
	s_waitcnt vmcnt(24)
	s_waitcnt lgkmcnt(0)
	s_barrier
	s_setprio 1
	s_waitcnt lgkmcnt(0)
	v_mfma_f32_16x16x32_bf16 v[126:129], v[130:133], v[200:203], v[126:129]
	v_mfma_f32_16x16x32_bf16 v[122:125], v[138:141], v[200:203], v[122:125]
	v_mfma_f32_16x16x32_bf16 v[110:113], v[130:133], v[208:211], v[110:113]
	v_mfma_f32_16x16x32_bf16 v[106:109], v[138:141], v[208:211], v[106:109]
	v_mfma_f32_16x16x32_bf16 v[94:97], v[130:133], v[216:219], v[94:97]
	v_mfma_f32_16x16x32_bf16 v[90:93], v[138:141], v[216:219], v[90:93]
	v_mfma_f32_16x16x32_bf16 v[78:81], v[130:133], v[224:227], v[78:81]
	v_mfma_f32_16x16x32_bf16 v[74:77], v[138:141], v[224:227], v[74:77]
	v_mfma_f32_16x16x32_bf16 v[126:129], v[134:137], v[204:207], v[126:129]
	v_mfma_f32_16x16x32_bf16 v[122:125], v[142:145], v[204:207], v[122:125]
	v_mfma_f32_16x16x32_bf16 v[110:113], v[134:137], v[212:215], v[110:113]
	v_mfma_f32_16x16x32_bf16 v[106:109], v[142:145], v[212:215], v[106:109]
	v_mfma_f32_16x16x32_bf16 v[94:97], v[134:137], v[220:223], v[94:97]
	v_mfma_f32_16x16x32_bf16 v[90:93], v[142:145], v[220:223], v[90:93]
	v_mfma_f32_16x16x32_bf16 v[78:81], v[134:137], v[228:231], v[78:81]
	v_mfma_f32_16x16x32_bf16 v[74:77], v[142:145], v[228:231], v[74:77]
	s_setprio 0
	s_setprio 1
	v_mfma_f32_16x16x32_bf16 v[118:121], v[172:175], v[200:203], v[118:121]
	v_mfma_f32_16x16x32_bf16 v[114:117], v[192:195], v[200:203], v[114:117]
	v_mfma_f32_16x16x32_bf16 v[102:105], v[172:175], v[208:211], v[102:105]
	v_mfma_f32_16x16x32_bf16 v[98:101], v[192:195], v[208:211], v[98:101]
	v_mfma_f32_16x16x32_bf16 v[86:89], v[172:175], v[216:219], v[86:89]
	v_mfma_f32_16x16x32_bf16 v[82:85], v[192:195], v[216:219], v[82:85]
	v_mfma_f32_16x16x32_bf16 v[70:73], v[172:175], v[224:227], v[70:73]
	v_mfma_f32_16x16x32_bf16 v[66:69], v[192:195], v[224:227], v[66:69]
	v_mfma_f32_16x16x32_bf16 v[118:121], v[176:179], v[204:207], v[118:121]
	v_mfma_f32_16x16x32_bf16 v[114:117], v[196:199], v[204:207], v[114:117]
	v_mfma_f32_16x16x32_bf16 v[102:105], v[176:179], v[212:215], v[102:105]
	v_mfma_f32_16x16x32_bf16 v[98:101], v[196:199], v[212:215], v[98:101]
	v_mfma_f32_16x16x32_bf16 v[86:89], v[176:179], v[220:223], v[86:89]
	v_mfma_f32_16x16x32_bf16 v[82:85], v[196:199], v[220:223], v[82:85]
	v_mfma_f32_16x16x32_bf16 v[70:73], v[176:179], v[228:231], v[70:73]
	v_mfma_f32_16x16x32_bf16 v[66:69], v[196:199], v[228:231], v[66:69]
	s_setprio 0
	s_barrier
; #define PG8_STAGE(bufoff, gbase, voff) do { _Pragma("unroll") for (int _i = 0; _i < 2; ++_i) \
;         __builtin_amdgcn_global_load_lds((const unsigned*)((const char*)(gbase) + (voff)[_i]), (PG8_LAS unsigned*)(lds + (bufoff) + ldsw + _i * 8192), 16, 0, 0); } while (0)
; #define PG8_LDA(dst, b, h) do { _Pragma("unroll") for (int m = 0; m < 4; ++m) _Pragma("unroll") for (int k = 0; k < 2; ++k) dst[m][k] = *(const PG8_LAS bf16x8*)(lds + PG8_SA(b, h) + aoff + m * 2048 + k * 1024); } while (0)
; #define PG8_MMA(ai, bj, At, Bt) do { __builtin_amdgcn_s_setprio(1); _Pragma("unroll") for (int m = 0; m < 4; ++m) _Pragma("unroll") for (int n = 0; n < 2; ++n) _Pragma("unroll") for (int k = 0; k < 2; ++k) \
;         acc[ai][bj][m][n] = __builtin_amdgcn_mfma_f32_16x16x32_bf16(Bt[n][k], At[m][k], acc[ai][bj][m][n], 0, 0, 0); __builtin_amdgcn_s_setprio(0); } while (0)
; #define PG8_WAIT_V(n) asm volatile("s_waitcnt vmcnt(" #n ")" ::: "memory")
; #define PG8_WAIT_L(n) asm volatile("s_waitcnt lgkmcnt(" #n ")" ::: "memory")
; #define PG8_BAR __builtin_amdgcn_s_barrier()
; #define PG8_SCHED __builtin_amdgcn_sched_barrier(0)
; template <class Epi, class Sched, bool ALIGN_EPI = false, bool SP2 = false>
; __device__ __forceinline__ void gemm_phase(PG8_LAS unsigned char* lds, const Gemm g, const Sched& S, const Epi& E) {
;     ...
;             PG8_LDA(At, 1, 1); PG8_STAGE(PG8_SB(1, 0), b3, voffB); PG8_STAGE(PG8_SB(1, 1), b3 + hstep, voffB); PG8_STAGE(PG8_SA(1, 0), a3, voffA);
;             PG8_WAIT_V(8); PG8_WAIT_L(0); PG8_BAR; PG8_MMA(1, 0, At, B0); PG8_MMA(1, 1, At, B1); PG8_BAR; PG8_SCHED;
	s_add_i32 s64, s94, s72
	v_lshl_add_u64 v[232:233], v[232:233], 0, s[12:13]
	s_mov_b32 m0, s64
	ds_read_b128 v[200:203], v185 offset:49152
	ds_read_b128 v[204:207], v185 offset:50176
	ds_read_b128 v[208:211], v185 offset:51200
	ds_read_b128 v[212:215], v185 offset:52224
	ds_read_b128 v[216:219], v185 offset:53248
	ds_read_b128 v[220:223], v185 offset:54272
	ds_read_b128 v[224:227], v185 offset:55296
	ds_read_b128 v[228:231], v185 offset:56320
	global_load_lds_dwordx4 v[232:233], off
	s_add_i32 m0, s64, 0x2000
	s_add_u32 s50, s50, 0x40080
	v_lshl_add_u64 v[232:233], v[234:235], 0, s[12:13]
	s_addc_u32 s51, s51, 0
	s_add_i32 s64, s95, s72
	global_load_lds_dwordx4 v[232:233], off
	v_lshl_add_u64 v[232:233], s[50:51], 0, v[148:149]
	s_mov_b32 m0, s64
	s_nop 0
	global_load_lds_dwordx4 v[232:233], off
	v_lshl_add_u64 v[232:233], s[50:51], 0, v[152:153]
	s_add_i32 m0, s64, 0x2000
	s_nop 0
	global_load_lds_dwordx4 v[232:233], off
	v_lshl_add_u64 v[232:233], v[236:237], 0, s[12:13]
	s_mov_b32 m0, s82
	s_nop 0
	global_load_lds_dwordx4 v[232:233], off
	v_lshl_add_u64 v[232:233], v[238:239], 0, s[12:13]
	s_mov_b32 m0, s83
	s_nop 0
	global_load_lds_dwordx4 v[232:233], off
	s_waitcnt vmcnt(8)
	s_waitcnt lgkmcnt(0)
	s_barrier
	s_setprio 1
	s_waitcnt lgkmcnt(0)
	v_mfma_f32_16x16x32_bf16 v[62:65], v[130:133], v[200:203], v[62:65]
	v_mfma_f32_16x16x32_bf16 v[58:61], v[138:141], v[200:203], v[58:61]
	v_mfma_f32_16x16x32_bf16 v[46:49], v[130:133], v[208:211], v[46:49]
	v_mfma_f32_16x16x32_bf16 v[42:45], v[138:141], v[208:211], v[42:45]
	v_mfma_f32_16x16x32_bf16 v[30:33], v[130:133], v[216:219], v[30:33]
	v_mfma_f32_16x16x32_bf16 v[26:29], v[138:141], v[216:219], v[26:29]
	v_mfma_f32_16x16x32_bf16 v[14:17], v[130:133], v[224:227], v[14:17]
	v_mfma_f32_16x16x32_bf16 v[10:13], v[138:141], v[224:227], v[10:13]
	v_mfma_f32_16x16x32_bf16 v[62:65], v[134:137], v[204:207], v[62:65]
	v_mfma_f32_16x16x32_bf16 v[58:61], v[142:145], v[204:207], v[58:61]
	v_mfma_f32_16x16x32_bf16 v[46:49], v[134:137], v[212:215], v[46:49]
	v_mfma_f32_16x16x32_bf16 v[42:45], v[142:145], v[212:215], v[42:45]
	v_mfma_f32_16x16x32_bf16 v[30:33], v[134:137], v[220:223], v[30:33]
	v_mfma_f32_16x16x32_bf16 v[26:29], v[142:145], v[220:223], v[26:29]
	v_mfma_f32_16x16x32_bf16 v[14:17], v[134:137], v[228:231], v[14:17]
	v_mfma_f32_16x16x32_bf16 v[10:13], v[142:145], v[228:231], v[10:13]
	s_setprio 0
	s_setprio 1
	v_mfma_f32_16x16x32_bf16 v[54:57], v[172:175], v[200:203], v[54:57]
	v_mfma_f32_16x16x32_bf16 v[50:53], v[192:195], v[200:203], v[50:53]
	v_mfma_f32_16x16x32_bf16 v[38:41], v[172:175], v[208:211], v[38:41]
	v_mfma_f32_16x16x32_bf16 v[34:37], v[192:195], v[208:211], v[34:37]
	v_mfma_f32_16x16x32_bf16 v[22:25], v[172:175], v[216:219], v[22:25]
	v_mfma_f32_16x16x32_bf16 v[18:21], v[192:195], v[216:219], v[18:21]
	v_mfma_f32_16x16x32_bf16 v[6:9], v[172:175], v[224:227], v[6:9]
	v_mfma_f32_16x16x32_bf16 v[2:5], v[192:195], v[224:227], v[2:5]
	v_mfma_f32_16x16x32_bf16 v[54:57], v[176:179], v[204:207], v[54:57]
	v_mfma_f32_16x16x32_bf16 v[50:53], v[196:199], v[204:207], v[50:53]
	v_mfma_f32_16x16x32_bf16 v[38:41], v[176:179], v[212:215], v[38:41]
	v_mfma_f32_16x16x32_bf16 v[34:37], v[196:199], v[212:215], v[34:37]
	v_mfma_f32_16x16x32_bf16 v[22:25], v[176:179], v[220:223], v[22:25]
	v_mfma_f32_16x16x32_bf16 v[18:21], v[196:199], v[220:223], v[18:21]
	v_mfma_f32_16x16x32_bf16 v[6:9], v[176:179], v[228:231], v[6:9]
	v_mfma_f32_16x16x32_bf16 v[2:5], v[196:199], v[228:231], v[2:5]
	s_setprio 0
	s_barrier
	s_add_i32 s93, s93, 2
	s_add_u32 s48, s48, 0x100
	s_addc_u32 s49, s49, 0
	s_add_u32 s41, s41, 0x100
	s_addc_u32 s92, s92, 0
	s_branch .LBB0_162
